# P2 K/V register prefetch two units ahead (second landing set v208-v239, parity-selected commit/issue), Q and bias one ahead; on top of the fused P9
# speedup vs baseline: 1.0062x; 1.0062x over previous
; #define LAS __attribute__((address_space(3)))
; __device__ __forceinline__ void attn_issue(AttnRegs& R, const AttnUnit& u, int blk, bool with_q, const bf16* qkv, const float* bias2) {
;     const int tid = threadIdx.x, lane = tid & 63, w = tid >> 6;
;     const int L = 4096 >> (2 * u.g), gh = u.g * 8 + u.h;
;     const int ch = tid & 15, r0 = tid >> 4;
;     if (with_q) R.tabv = bias2[gh * 192 + (tid < 192 ? tid : 0)];
;     const size_t rb = (size_t)(u.r * L + blk * 128 + r0) * 128 + ch * 8;
;     const bf16* kp = attn_plane(qkv, 1, u) + rb; const bf16* vp = attn_plane(qkv, 2, u) + rb;
; #pragma unroll
;     for (int j = 0; j < 4; ++j) { R.kr[j] = *(const v4u*)(kp + (size_t)j * 32 * 128); R.vr[j] = *(const v4u*)(vp + (size_t)j * 32 * 128); }
; __global__ void __launch_bounds__(NTHREADS, 2) fwd_megakernel(Args args) {
;     ...
;         const int per = (NUNITS + G - 1) / G;
;         const int u0 = vcu * per, u1 = (u0 + per < NUNITS) ? u0 + per : NUNITS;
;         { const v4u z = {0u, 0u, 0u, 0u}; for (int i = threadIdx.x; i < 8192; i += NTHREADS) *(LAS v4u*)(lds + 16 * i) = z; }
;         asm volatile("s_waitcnt lgkmcnt(0)" ::: "memory"); __builtin_amdgcn_s_barrier(); asm volatile("" ::: "memory");
;         AttnRegs R;
;         if (u0 < u1) { const AttnUnit un = attn_decode(u0);
;             if (un.n > 0) { attn_issue(R, un, un.n - 1, false, PROJ, BIAS2); attn_commit(R, un.n - 1, false, lds); }
;             attn_issue(R, un, un.n, true, PROJ, BIAS2); }
.LBB0_145:
	s_add_u32 s0, s40, 0x3fc00000
	s_addc_u32 s1, s41, 0
	s_add_u32 s33, s40, 0xbc00000
	s_addc_u32 s46, s41, 0
	s_add_u32 s47, s38, 0x8000000
	s_addc_u32 s64, s39, 0
	s_add_i32 s4, s59, s10
	s_or_b32 s4, s4, s6
	s_ashr_i32 s5, s4, 31
	s_lshl_b64 s[4:5], s[4:5], 20
	v_lshrrev_b32_e32 v1, 2, v178
	s_add_u32 s4, s18, s4
	v_and_b32_e32 v33, 0xf0, v1
	s_addc_u32 s5, s19, s5
	v_or_b32_e32 v1, v33, v92
	s_add_i32 s8, s9, s8
	v_add_lshl_u32 v80, s8, v1, 8
	v_mov_b32_e32 v81, 0
	v_lshl_add_u64 v[2:3], s[4:5], 0, v[80:81]
	s_add_i32 s4, s58, s10
	v_lshrrev_b32_e32 v1, 1, v178
	s_ashr_i32 s5, s4, 31
	v_and_b32_e32 v34, 24, v1
	s_lshl_b64 s[4:5], s[4:5], 20
	v_lshlrev_b32_e32 v80, 1, v34
	v_add_u32_e32 v0, s9, v0
	s_add_u32 s4, s18, s4
	v_lshl_add_u64 v[2:3], v[2:3], 0, v[80:81]
	v_lshl_or_b32 v80, v0, 7, v91
	s_addc_u32 s5, s19, s5
	v_lshl_add_u64 v[12:13], v[80:81], 1, s[4:5]
	s_mov_b32 s65, 0x18006000
	v_add_co_u32_e32 v0, vcc, s65, v12
	s_mov_b32 s66, 0xc006000
	s_nop 0
	v_addc_co_u32_e32 v1, vcc, 0, v13, vcc
	global_load_dwordx4 v[48:51], v[2:3], off offset:192
	global_load_dwordx4 v[52:55], v[2:3], off offset:128
	global_load_dwordx4 v[56:59], v[2:3], off offset:64
	global_load_dwordx4 v[60:63], v[2:3], off
	v_add_co_u32_e32 v2, vcc, s66, v12
	s_mov_b32 s67, 0x18004000
	s_nop 0
	v_addc_co_u32_e32 v3, vcc, 0, v13, vcc
	v_add_co_u32_e32 v4, vcc, s67, v12
	s_mov_b32 s68, 0xc004000
	s_nop 0
	v_addc_co_u32_e32 v5, vcc, 0, v13, vcc
	v_add_co_u32_e32 v6, vcc, s68, v12
	s_mov_b32 s69, 0x18002000
	s_nop 0
	v_addc_co_u32_e32 v7, vcc, 0, v13, vcc
	v_add_co_u32_e32 v8, vcc, s69, v12
	s_mov_b32 s70, 0xc002000
	s_nop 0
	v_addc_co_u32_e32 v9, vcc, 0, v13, vcc
	s_lshl_b32 s4, s7, 3
	v_add_co_u32_e32 v10, vcc, s70, v12
	s_or_b32 s4, s4, s6
	s_movk_i32 s5, 0xc0
	v_addc_co_u32_e32 v11, vcc, 0, v13, vcc
	s_brev_b32 s71, 24
	s_mul_i32 s6, s4, 0xc0
	v_cmp_gt_u32_e64 s[4:5], s5, v178
	v_add_co_u32_e32 v14, vcc, s71, v12
	s_nop 0
	v_cndmask_b32_e64 v95, 0, v178, s[4:5]
	v_addc_co_u32_e32 v15, vcc, 0, v13, vcc
	s_brev_b32 s72, 48
	v_add_u32_e32 v36, s6, v95
	v_add_co_u32_e32 v12, vcc, s72, v12
	v_ashrrev_i32_e32 v37, 31, v36
	s_nop 0
	v_addc_co_u32_e32 v13, vcc, 0, v13, vcc
	v_lshl_add_u64 v[36:37], v[36:37], 2, s[56:57]
	global_load_dwordx4 v[28:31], v[0:1], off
	s_nop 0
	global_load_dwordx4 v[0:3], v[2:3], off
	s_nop 0
	global_load_dwordx4 v[16:19], v[4:5], off
	s_nop 0
	global_load_dwordx4 v[4:7], v[6:7], off
	s_nop 0
	global_load_dwordx4 v[20:23], v[8:9], off
	s_nop 0
	global_load_dwordx4 v[8:11], v[10:11], off
	s_nop 0
	global_load_dwordx4 v[24:27], v[14:15], off
	s_nop 0
	global_load_dwordx4 v[12:15], v[12:13], off
	v_lshlrev_b32_e32 v35, 2, v178
	global_load_dword v125, v[36:37], off
	s_add_i32 s6, 0, 0x20000
	v_add_u32_e32 v97, s6, v35
	v_and_b32_e32 v102, 12, v35
	v_lshrrev_b32_e32 v35, 1, v92
	v_bfe_u32 v99, v178, 4, 2
	v_and_b32_e32 v35, 2, v35
	v_or_b32_e32 v98, v33, v92
	v_lshrrev_b32_e32 v33, 2, v92
	v_bitop3_b32 v36, v35, v99, v102 bitop3:0x36
	v_or_b32_e32 v104, 4, v99
	v_lshlrev_b32_e32 v100, 3, v33
	v_lshlrev_b32_e32 v103, 4, v36
	v_bitop3_b32 v36, v35, v104, v102 bitop3:0x36
	v_or_b32_e32 v106, 8, v99
	v_or_b32_e32 v108, 12, v99
	v_lshl_or_b32 v111, v99, 3, v33
	v_lshlrev_b32_e32 v33, 1, v90
	v_lshlrev_b32_e32 v105, 4, v36
	v_bitop3_b32 v36, v35, v106, v102 bitop3:0x36
	v_bitop3_b32 v35, v35, v108, v102 bitop3:0x36
	v_and_b32_e32 v113, 12, v178
	v_and_b32_e32 v33, 2, v33
	v_lshlrev_b32_e32 v109, 4, v35
	v_bfe_u32 v112, v178, 1, 1
	v_or_b32_e32 v35, v33, v113
	v_and_b32_e32 v114, 8, v32
	v_or_b32_e32 v32, v35, v112
	v_or_b32_e32 v116, 2, v112
	v_lshlrev_b32_e32 v115, 4, v32
	v_bitop3_b32 v32, v33, v116, v113 bitop3:0x36
	v_or_b32_e32 v118, 4, v112
	v_lshlrev_b32_e32 v117, 4, v32
	v_bitop3_b32 v32, v33, v118, v113 bitop3:0x36
	v_or_b32_e32 v120, 6, v112
	v_lshlrev_b32_e32 v119, 4, v32
	v_bitop3_b32 v32, v33, v120, v113 bitop3:0x36
	v_or_b32_e32 v122, 8, v112
	v_lshlrev_b32_e32 v121, 4, v32
	v_bitop3_b32 v32, v33, v122, v113 bitop3:0x36
	v_or_b32_e32 v124, 10, v112
	v_lshlrev_b32_e32 v123, 4, v32
	v_bitop3_b32 v32, v33, v124, v113 bitop3:0x36
	v_or_b32_e32 v127, 12, v112
	v_lshlrev_b32_e32 v126, 4, v32
	v_bitop3_b32 v32, v33, v127, v113 bitop3:0x36
	v_or_b32_e32 v129, 14, v112
	v_lshlrev_b32_e32 v128, 4, v32
	v_bitop3_b32 v32, v33, v129, v113 bitop3:0x36
	v_lshlrev_b32_e32 v130, 4, v32
	v_lshlrev_b32_e32 v32, 2, v99
	v_lshlrev_b32_e32 v84, 1, v32
	v_mbcnt_lo_u32_b32 v32, -1, 0
	s_mov_b32 s9, 0
	v_or_b32_e32 v96, 0x4000, v93
	v_and_b32_e32 v101, 3, v178
	v_lshlrev_b32_e32 v107, 4, v36
	v_lshl_add_u32 v110, v99, 5, s6
	v_cmp_eq_u32_e64 s[6:7], 0, v99
	s_add_i32 s73, 0, 0x10000
	v_lshlrev_b32_e32 v82, 1, v34
	s_mov_b32 s74, 0xf149f2ca
	v_mov_b32_e32 v131, 0xf149f2ca
	v_mbcnt_hi_u32_b32 v132, -1, v32
	v_lshlrev_b32_e32 v240, 4, v178
	v_add_u32_e32 v241, 0x2000, v240
	v_add_u32_e32 v242, 0x4000, v240
	v_add_u32_e32 v243, 0x6000, v240
	s_mov_b32 s94, 0
	s_add_i32 s97, s11, 1
	s_cmp_ge_i32 s97, s29
	s_cbranch_scc1 .Lp2kv_pro_skip
	s_lshr_b32 s88, s97, 8
	s_mul_hi_u32 s32, s88, 0x55555556
	s_mul_i32 s92, s32, 3
	s_sub_i32 s88, s88, s92
	s_lshl_b32 s88, s88, 6
	s_lshl_b32 s32, s32, 3
	s_add_i32 s88, s88, s32
	s_bfe_u32 s32, s97, 0x30005
	s_add_i32 s88, s88, s32
	s_addk_i32 s88, 0xc0
	s_lshl_b32 s88, s88, 20
	s_and_b32 s32, s97, 31
	s_lshl_b32 s32, s32, 15
	s_add_i32 s88, s88, s32
	s_add_u32 s92, s18, s88
	s_addc_u32 s93, s19, 0
	s_add_u32 s98, s92, 0xc000000
	s_addc_u32 s99, s93, 0
	global_load_dwordx4 v[220:223], v240, s[92:93]
	global_load_dwordx4 v[232:235], v240, s[98:99]
	global_load_dwordx4 v[216:219], v241, s[92:93]
	global_load_dwordx4 v[228:231], v241, s[98:99]
	global_load_dwordx4 v[212:215], v242, s[92:93]
	global_load_dwordx4 v[224:227], v242, s[98:99]
	global_load_dwordx4 v[208:211], v243, s[92:93]
	global_load_dwordx4 v[236:239], v243, s[98:99]
; #define LAS __attribute__((address_space(3)))
; __device__ __forceinline__ void attn_commit(const AttnRegs& R, int blk, bool with_tab, LAS unsigned char* lds) {
;     const int tid = threadIdx.x; const int ch = tid & 15, r0 = tid >> 4;
;     LAS unsigned char* Ks = lds; LAS unsigned char* Vs = lds + 65536; LAS float* tab = (LAS float*)(lds + LDS_TAB);
; #pragma unroll
;     for (int j = 0; j < 4; ++j) { const unsigned row = (blk & 1) * 128 + r0 + 32 * j; *(LAS v4u*)(Ks + off_b(row, ch)) = R.kr[j]; *(LAS v4u*)(Vs + off_b(row, ch)) = R.vr[j]; }
;     if (with_tab && tid < 192) tab[tid] = R.tabv;
; __global__ void __launch_bounds__(NTHREADS, 2) fwd_megakernel(Args args) {
;     ...
;             attn_commit(R, u.n, true, lds);
;             bf16x8 qf[4];
; #pragma unroll
;             for (int s4 = 0; s4 < 4; ++s4) qf[s4] = R.qf[s4];
;             asm volatile("s_waitcnt lgkmcnt(0)" ::: "memory"); __builtin_amdgcn_s_barrier(); asm volatile("" ::: "memory");
.Lp2kv_pro_skip:
	s_waitcnt vmcnt(0)
	s_branch .LBB0_147
.LBB0_146:
	s_or_b64 exec, exec, s[60:61]
	s_waitcnt lgkmcnt(0)
	s_barrier
	s_add_i32 s97, s75, 1
	s_cmp_ge_i32 s97, s29
	s_cbranch_scc1 .Lp2_wait_tail
	s_waitcnt vmcnt(17)
	s_branch .Lp2_wait_done
.Lp2_wait_tail:
	s_waitcnt vmcnt(8)
.Lp2_wait_done:
	s_xor_b32 s94, s94, 1
	v_mov_b64_e32 v[62:63], v[34:35]
	v_mov_b64_e32 v[58:59], v[38:39]
	v_mov_b64_e32 v[54:55], v[42:43]
	v_mov_b64_e32 v[50:51], v[46:47]
	s_and_b64 vcc, exec, s[58:59]
	v_mov_b64_e32 v[60:61], v[32:33]
	v_mov_b64_e32 v[56:57], v[36:37]
	v_mov_b64_e32 v[52:53], v[40:41]
	v_mov_b64_e32 v[48:49], v[44:45]
	s_mov_b32 s11, s75
	s_cbranch_vccnz .LBB0_153
.LBB0_147:
	s_cmp_eq_u32 s94, 0
	s_cbranch_scc1 .Lp2_commit_r1
	s_ashr_i32 s8, s11, 8
	s_mul_hi_i32 s10, s8, 0x55555556
	s_lshr_b32 s30, s10, 31
	s_add_i32 s62, s10, s30
	s_mul_i32 s10, s62, 3
	s_sub_i32 s10, s8, s10
	s_lshl_b32 s8, s10, 1
	s_lshr_b32 s30, 32, s8
	s_and_b32 s63, s11, 31
	s_add_i32 s30, s30, -1
	s_and_b32 s84, s30, s63
	s_lshl_b32 s81, s84, 7
	s_and_b32 s30, s81, 0x80
	v_or_b32_e32 v32, s30, v90
	v_lshlrev_b32_e32 v33, 8, v32
	v_or_b32_e32 v34, v33, v93
	v_add_u32_e32 v35, 0, v34
	v_add_u32_e32 v34, s73, v34
	ds_write_b128 v34, v[232:235]
	v_add_u32_e32 v34, 32, v32
	ds_write_b128 v35, v[220:223]
	v_lshlrev_b32_e32 v35, 8, v34
	v_lshlrev_b32_e32 v34, 2, v34
	v_and_b32_e32 v34, 12, v34
	v_bitop3_b32 v34, v34, v92, v94 bitop3:0x36
	v_lshl_or_b32 v34, v34, 4, v35
	v_add_u32_e32 v35, 0, v34
	v_add_u32_e32 v34, s73, v34
	ds_write_b128 v34, v[228:231]
	v_or_b32_e32 v34, v33, v96
	v_add3_u32 v33, v33, v93, 0
	ds_write_b128 v35, v[216:219]
	ds_write_b128 v33, v[212:215] offset:16384
	v_add_u32_e32 v33, s73, v34
	v_add_u32_e32 v32, 0x60, v32
	ds_write_b128 v33, v[224:227]
	v_lshlrev_b32_e32 v33, 8, v32
	v_lshlrev_b32_e32 v32, 2, v32
	v_and_b32_e32 v32, 12, v32
	v_bitop3_b32 v32, v32, v92, v94 bitop3:0x36
	v_lshl_or_b32 v32, v32, 4, v33
	v_add_u32_e32 v33, 0, v32
	v_add_u32_e32 v32, s73, v32
	ds_write_b128 v33, v[208:211]
	ds_write_b128 v32, v[236:239]
	s_branch .Lp2_commit_done

; #define LAS __attribute__((address_space(3)))
; __device__ __forceinline__ void attn_issue(AttnRegs& R, const AttnUnit& u, int blk, bool with_q, const bf16* qkv, const float* bias2) {
;     const int tid = threadIdx.x, lane = tid & 63, w = tid >> 6;
;     const int L = 4096 >> (2 * u.g), gh = u.g * 8 + u.h;
;     const int ch = tid & 15, r0 = tid >> 4;
;     if (with_q) R.tabv = bias2[gh * 192 + (tid < 192 ? tid : 0)];
;     const size_t rb = (size_t)(u.r * L + blk * 128 + r0) * 128 + ch * 8;
;     const bf16* kp = attn_plane(qkv, 1, u) + rb; const bf16* vp = attn_plane(qkv, 2, u) + rb;
; #pragma unroll
;     for (int j = 0; j < 4; ++j) { R.kr[j] = *(const v4u*)(kp + (size_t)j * 32 * 128); R.vr[j] = *(const v4u*)(vp + (size_t)j * 32 * 128); }
;     if (with_q) {
;         const int qi = 16 * w + (lane & 15), kg = lane >> 4;
;         const bf16* qp = attn_plane(qkv, 0, u) + (size_t)(u.r * L + u.n * 128 + qi) * 128 + 8 * kg;
; #pragma unroll
;         for (int s = 0; s < 4; ++s) R.qf[s] = *(const bf16x8*)(qp + 32 * s);
;     }
; }
; __device__ __forceinline__ void attn_compute(LAS unsigned char* lds, const bf16x8 (&qf)[4], const AttnUnit& u, bf16* og, float* lse) {
;     ...
;     for (int kk = 0; kk < 5; ++kk) {
;         const int ks = ks0 + kk;
;         bf16x8 kf[2][4];
; #pragma unroll
;         for (int T = 0; T < 2; ++T)
; #pragma unroll
;             for (int s = 0; s < 4; ++s) kf[T][s] = *(const LAS bf16x8*)(Ks + (off_b(32 * ks + krow + 4 * T, 4 * s + kg) ^ par));
; #pragma unroll
;         for (int T = 0; T < 2; ++T) {
;             f32x4 a = {0.f, 0.f, 0.f, 0.f};
; #pragma unroll
;             for (int s = 0; s < 4; ++s) a = __builtin_amdgcn_mfma_f32_16x16x32_bf16(kf[T][s], qf[s], a, 0, 0, 0);
.Lp2_commit_done:
	s_and_saveexec_b64 s[58:59], s[4:5]
	s_cbranch_execz .LBB0_149
	ds_write_b32 v97, v125
.LBB0_149:
	s_or_b64 exec, exec, s[58:59]
	s_add_i32 s75, s11, 1
	s_waitcnt lgkmcnt(0)
	s_barrier
	s_cmp_ge_i32 s75, s29
	s_cselect_b64 s[58:59], -1, 0
	v_mov_b64_e32 v[32:33], v[60:61]
	v_mov_b64_e32 v[36:37], v[56:57]
	v_mov_b64_e32 v[40:41], v[52:53]
	v_mov_b64_e32 v[44:45], v[48:49]
	s_and_b64 vcc, exec, s[58:59]
	v_mov_b64_e32 v[34:35], v[62:63]
	v_mov_b64_e32 v[38:39], v[58:59]
	v_mov_b64_e32 v[42:43], v[54:55]
	v_mov_b64_e32 v[46:47], v[50:51]
	s_cbranch_vccnz .LBB0_151
	s_lshr_b32 s88, s75, 8
	s_mul_hi_u32 s32, s88, 0x55555556
	s_mul_i32 s97, s32, 3
	s_sub_i32 s88, s88, s97
	s_bfe_u32 s97, s75, 0x30005
	s_lshl_b32 s30, s88, 3
	s_or_b32 s30, s30, s97
	s_mulk_i32 s30, 0xc0
	v_add_lshl_u32 v64, s30, v95, 2
	global_load_dword v125, v64, s[56:57]
	s_lshl_b32 s88, s88, 6
	s_lshl_b32 s32, s32, 3
	s_add_i32 s88, s88, s32
	s_add_i32 s88, s88, s97
	s_lshl_b32 s88, s88, 20
	s_and_b32 s32, s75, 31
	s_lshl_b32 s32, s32, 15
	s_add_i32 s88, s88, s32
	s_add_u32 s30, s18, s88
	s_addc_u32 s31, s19, 0
	v_lshl_add_u32 v65, v98, 8, v82
	global_load_dwordx4 v[32:35], v65, s[30:31]
	global_load_dwordx4 v[36:39], v65, s[30:31] offset:64
	global_load_dwordx4 v[40:43], v65, s[30:31] offset:128
	global_load_dwordx4 v[44:47], v65, s[30:31] offset:192
	s_add_i32 s97, s75, 1
	s_cmp_ge_i32 s97, s29
	s_cbranch_scc1 .Lp2_kv_done
	s_lshr_b32 s88, s97, 8
	s_mul_hi_u32 s32, s88, 0x55555556
	s_mul_i32 s92, s32, 3
	s_sub_i32 s88, s88, s92
	s_lshl_b32 s88, s88, 6
	s_lshl_b32 s32, s32, 3
	s_add_i32 s88, s88, s32
	s_bfe_u32 s32, s97, 0x30005
	s_add_i32 s88, s88, s32
	s_addk_i32 s88, 0xc0
	s_lshl_b32 s88, s88, 20
	s_and_b32 s32, s97, 31
	s_lshl_b32 s32, s32, 15
	s_add_i32 s88, s88, s32
	s_add_u32 s92, s18, s88
	s_addc_u32 s93, s19, 0
	s_add_u32 s98, s92, 0xc000000
	s_addc_u32 s99, s93, 0
	s_cmp_eq_u32 s94, 0
	s_cbranch_scc1 .Lp2_kv_r1
	global_load_dwordx4 v[220:223], v240, s[92:93]
	global_load_dwordx4 v[232:235], v240, s[98:99]
	global_load_dwordx4 v[216:219], v241, s[92:93]
	global_load_dwordx4 v[228:231], v241, s[98:99]
	global_load_dwordx4 v[212:215], v242, s[92:93]
	global_load_dwordx4 v[224:227], v242, s[98:99]
	global_load_dwordx4 v[208:211], v243, s[92:93]
	global_load_dwordx4 v[236:239], v243, s[98:99]
	s_branch .Lp2_kv_done
.Lp2_kv_r1:
	global_load_dwordx4 v[12:15], v240, s[92:93]
	global_load_dwordx4 v[24:27], v240, s[98:99]
	global_load_dwordx4 v[8:11], v241, s[92:93]
	global_load_dwordx4 v[20:23], v241, s[98:99]
	global_load_dwordx4 v[4:7], v242, s[92:93]
	global_load_dwordx4 v[16:19], v242, s[98:99]
	global_load_dwordx4 v[0:3], v243, s[92:93]
	global_load_dwordx4 v[28:31], v243, s[98:99]
.Lp2_kv_done:
.LBB0_151:
	s_bfe_u32 s76, s11, 0x30005
	s_sub_i32 s11, 5, s8
	s_lshr_b32 s11, s63, s11
	s_cmp_eq_u32 s10, 1
	s_cselect_b32 s30, s33, s47
	s_cselect_b32 s31, s46, s64
	s_cmp_eq_u32 s10, 0
	v_readfirstlane_b32 s85, v178
	s_cselect_b32 s61, s91, s31
	s_cselect_b32 s60, s90, s30
	s_lshr_b32 s86, s85, 2
	s_and_b32 s83, s86, 0x3fffffe0
	s_not_b32 s30, s63
	v_or_b32_e32 v80, s83, v100
	s_lshl_b32 s30, s30, 15
	v_or_b32_e32 v64, v80, v101
	s_and_b32 s77, s30, 0x8000
	v_lshlrev_b32_e32 v72, 8, v64
	v_bitop3_b32 v64, v72, s77, v103 bitop3:0x36
	v_bitop3_b32 v65, v72, s77, v105 bitop3:0x36
	v_add_u32_e32 v64, 0, v64
	v_add_u32_e32 v68, 0, v65
	ds_read_b128 v[64:67], v64
	ds_read_b128 v[68:71], v68
	s_waitcnt lgkmcnt(1)
	v_mfma_f32_16x16x32_bf16 v[64:67], v[64:67], v[60:63], 0
	v_bitop3_b32 v73, v72, s77, v107 bitop3:0x36
	v_bitop3_b32 v72, v72, s77, v109 bitop3:0x36
	v_add_u32_e32 v73, 0, v73
	v_add_u32_e32 v76, 0, v72
	v_or_b32_e32 v80, 4, v80
	ds_read_b128 v[72:75], v73
	ds_read_b128 v[76:79], v76
	v_or_b32_e32 v83, v80, v101
	v_bfe_u32 v80, v80, 2, 2
	s_waitcnt lgkmcnt(2)
	v_mfma_f32_16x16x32_bf16 v[64:67], v[68:71], v[56:59], v[64:67]
	v_bitop3_b32 v85, v80, v99, v102 bitop3:0x36
	v_bitop3_b32 v86, v80, v104, v102 bitop3:0x36
	v_lshlrev_b32_e32 v83, 8, v83
	v_lshlrev_b32_e32 v85, 4, v85
	v_lshlrev_b32_e32 v86, 4, v86
	v_bitop3_b32 v85, v85, s77, v83 bitop3:0x36
	v_bitop3_b32 v86, v86, s77, v83 bitop3:0x36
	v_add_u32_e32 v85, 0, v85
	v_add_u32_e32 v68, 0, v86
	s_waitcnt lgkmcnt(1)
	v_mfma_f32_16x16x32_bf16 v[64:67], v[72:75], v[52:55], v[64:67]
	ds_read_b128 v[86:89], v85
	ds_read_b128 v[134:137], v68
	v_bitop3_b32 v68, v80, v106, v102 bitop3:0x36
	v_lshlrev_b32_e32 v68, 4, v68
	v_bitop3_b32 v72, v68, s77, v83 bitop3:0x36
	s_waitcnt lgkmcnt(2)
	v_mfma_f32_16x16x32_bf16 v[68:71], v[76:79], v[48:51], v[64:67]
	v_bitop3_b32 v76, v80, v108, v102 bitop3:0x36
	v_lshlrev_b32_e32 v76, 4, v76
	v_bitop3_b32 v76, v76, s77, v83 bitop3:0x36
	v_add_u32_e32 v64, 0, v72
	ds_read_b128 v[64:67], v64
	s_waitcnt lgkmcnt(2)
	v_mfma_f32_16x16x32_bf16 v[72:75], v[86:89], v[60:63], 0
	v_add_u32_e32 v76, 0, v76
	ds_read_b128 v[76:79], v76
	s_add_i32 s82, s83, 32
	s_waitcnt lgkmcnt(2)
	v_mfma_f32_16x16x32_bf16 v[72:75], v[134:137], v[56:59], v[72:75]
	v_or_b32_e32 v80, s82, v100
	s_add_i32 s80, s83, 64
	s_add_i32 s79, s83, 0x60
	s_waitcnt lgkmcnt(1)
	v_mfma_f32_16x16x32_bf16 v[64:67], v[64:67], v[52:55], v[72:75]
	s_add_i32 s78, s83, 0x80
	s_ashr_i32 s63, s62, 31
	s_and_b32 s54, s86, 0x3ffffff0
	v_or_b32_e32 v72, v80, v101
	v_lshlrev_b32_e32 v83, 8, v72
	v_bitop3_b32 v72, v83, s77, v103 bitop3:0x36
	v_bitop3_b32 v73, v83, s77, v105 bitop3:0x36
	s_waitcnt lgkmcnt(0)
	v_mfma_f32_16x16x32_bf16 v[64:67], v[76:79], v[48:51], v[64:67]
	v_add_u32_e32 v72, 0, v72
	v_add_u32_e32 v76, 0, v73
	ds_read_b128 v[72:75], v72
	ds_read_b128 v[76:79], v76
	s_waitcnt lgkmcnt(1)
; #define LAS __attribute__((address_space(3)))
; __device__ __forceinline__ void attn_compute(LAS unsigned char* lds, const bf16x8 (&qf)[4], const AttnUnit& u, bf16* og, float* lse) {
;     ...
;     for (int kk = 0; kk < 5; ++kk) {
;         const int ks = ks0 + kk;
;         bf16x8 kf[2][4];
; #pragma unroll
;         for (int T = 0; T < 2; ++T)
; #pragma unroll
;             for (int s = 0; s < 4; ++s) kf[T][s] = *(const LAS bf16x8*)(Ks + (off_b(32 * ks + krow + 4 * T, 4 * s + kg) ^ par));
; #pragma unroll
;         for (int T = 0; T < 2; ++T) {
;             f32x4 a = {0.f, 0.f, 0.f, 0.f};
; #pragma unroll
;             for (int s = 0; s < 4; ++s) a = __builtin_amdgcn_mfma_f32_16x16x32_bf16(kf[T][s], qf[s], a, 0, 0, 0);
;             sc[kk][T] = a;
;         }
;     }
	v_mfma_f32_16x16x32_bf16 v[72:75], v[72:75], v[60:63], 0
	v_bitop3_b32 v85, v83, s77, v107 bitop3:0x36
	v_bitop3_b32 v83, v83, s77, v109 bitop3:0x36
	v_add_u32_e32 v85, 0, v85
	v_add_u32_e32 v83, 0, v83
	v_or_b32_e32 v80, 4, v80
	ds_read_b128 v[86:89], v85
	ds_read_b128 v[134:137], v83
	v_or_b32_e32 v83, v80, v101
	v_bfe_u32 v80, v80, 2, 2
	s_waitcnt lgkmcnt(2)
	v_mfma_f32_16x16x32_bf16 v[72:75], v[76:79], v[56:59], v[72:75]
	v_bitop3_b32 v85, v80, v99, v102 bitop3:0x36
	v_bitop3_b32 v133, v80, v104, v102 bitop3:0x36
	v_lshlrev_b32_e32 v83, 8, v83
	v_lshlrev_b32_e32 v85, 4, v85
	v_lshlrev_b32_e32 v133, 4, v133
	v_bitop3_b32 v85, v85, s77, v83 bitop3:0x36
	v_bitop3_b32 v133, v133, s77, v83 bitop3:0x36
	v_add_u32_e32 v85, 0, v85
	v_add_u32_e32 v76, 0, v133
	s_waitcnt lgkmcnt(1)
	v_mfma_f32_16x16x32_bf16 v[72:75], v[86:89], v[52:55], v[72:75]
	ds_read_b128 v[138:141], v85
	ds_read_b128 v[142:145], v76
	v_bitop3_b32 v76, v80, v106, v102 bitop3:0x36
	v_lshlrev_b32_e32 v76, 4, v76
	v_bitop3_b32 v85, v76, s77, v83 bitop3:0x36
	s_waitcnt lgkmcnt(2)
	v_mfma_f32_16x16x32_bf16 v[76:79], v[134:137], v[48:51], v[72:75]
	v_bitop3_b32 v80, v80, v108, v102 bitop3:0x36
	v_lshlrev_b32_e32 v80, 4, v80
	v_bitop3_b32 v80, v80, s77, v83 bitop3:0x36
	v_add_u32_e32 v72, 0, v85
	ds_read_b128 v[72:75], v72
	s_waitcnt lgkmcnt(2)
	v_mfma_f32_16x16x32_bf16 v[86:89], v[138:141], v[60:63], 0
	v_add_u32_e32 v80, 0, v80
	ds_read_b128 v[134:137], v80
	v_or_b32_e32 v80, s80, v100
	s_waitcnt lgkmcnt(2)
	v_mfma_f32_16x16x32_bf16 v[86:89], v[142:145], v[56:59], v[86:89]
	v_or_b32_e32 v83, v80, v101
	v_lshlrev_b32_e32 v83, 8, v83
	v_bitop3_b32 v85, v83, s77, v103 bitop3:0x36
	s_waitcnt lgkmcnt(1)
	v_mfma_f32_16x16x32_bf16 v[72:75], v[72:75], v[52:55], v[86:89]
	v_add_u32_e32 v85, 0, v85
	v_or_b32_e32 v80, 4, v80
	s_lshl_b64 s[62:63], s[62:63], 12
	v_bitop3_b32 v86, v83, s77, v105 bitop3:0x36
	s_waitcnt lgkmcnt(0)
	v_mfma_f32_16x16x32_bf16 v[72:75], v[134:137], v[48:51], v[72:75]
	v_add_u32_e32 v133, 0, v86
	ds_read_b128 v[86:89], v85
	ds_read_b128 v[134:137], v133
	v_bitop3_b32 v85, v83, s77, v107 bitop3:0x36
	s_waitcnt lgkmcnt(1)
	v_mfma_f32_16x16x32_bf16 v[86:89], v[86:89], v[60:63], 0
	v_bitop3_b32 v83, v83, s77, v109 bitop3:0x36
	v_add_u32_e32 v85, 0, v85
	v_add_u32_e32 v83, 0, v83
	ds_read_b128 v[138:141], v85
	ds_read_b128 v[142:145], v83
	v_or_b32_e32 v83, v80, v101
	v_bfe_u32 v80, v80, 2, 2
	v_bitop3_b32 v85, v80, v99, v102 bitop3:0x36
	s_waitcnt lgkmcnt(2)
	v_mfma_f32_16x16x32_bf16 v[86:89], v[134:137], v[56:59], v[86:89]
	v_lshlrev_b32_e32 v83, 8, v83
	v_lshlrev_b32_e32 v85, 4, v85
	v_bitop3_b32 v133, v80, v104, v102 bitop3:0x36
	v_bitop3_b32 v85, v85, s77, v83 bitop3:0x36
	v_lshlrev_b32_e32 v133, 4, v133
	v_add_u32_e32 v85, 0, v85
	v_bitop3_b32 v133, v133, s77, v83 bitop3:0x36
	v_add_u32_e32 v133, 0, v133
	ds_read_b128 v[134:137], v85
	ds_read_b128 v[146:149], v133
	s_waitcnt lgkmcnt(3)
	v_mfma_f32_16x16x32_bf16 v[86:89], v[138:141], v[52:55], v[86:89]
	v_bitop3_b32 v85, v80, v106, v102 bitop3:0x36
	v_lshlrev_b32_e32 v85, 4, v85
	v_bitop3_b32 v85, v85, s77, v83 bitop3:0x36
	v_add_u32_e32 v85, 0, v85
	s_waitcnt lgkmcnt(2)
	v_mfma_f32_16x16x32_bf16 v[138:141], v[142:145], v[48:51], v[86:89]
	v_bitop3_b32 v80, v80, v108, v102 bitop3:0x36
	v_lshlrev_b32_e32 v80, 4, v80
	v_bitop3_b32 v80, v80, s77, v83 bitop3:0x36
	ds_read_b128 v[86:89], v85
	s_waitcnt lgkmcnt(2)
	v_mfma_f32_16x16x32_bf16 v[134:137], v[134:137], v[60:63], 0
	v_add_u32_e32 v80, 0, v80
	ds_read_b128 v[142:145], v80
	v_or_b32_e32 v80, s79, v100
	s_waitcnt lgkmcnt(2)
	v_mfma_f32_16x16x32_bf16 v[134:137], v[146:149], v[56:59], v[134:137]
	v_or_b32_e32 v83, v80, v101
	v_lshlrev_b32_e32 v83, 8, v83
	v_bitop3_b32 v85, v83, s77, v103 bitop3:0x36
	s_waitcnt lgkmcnt(1)
	v_mfma_f32_16x16x32_bf16 v[86:89], v[86:89], v[52:55], v[134:137]
	v_add_u32_e32 v85, 0, v85
	v_or_b32_e32 v80, 4, v80
	s_andn2_b32 s30, 16, s86
	s_waitcnt lgkmcnt(0)
	v_mfma_f32_16x16x32_bf16 v[134:137], v[142:145], v[48:51], v[86:89]
	s_cmp_eq_u32 s84, 0
	s_nop 1
	v_bitop3_b32 v86, v83, s77, v105 bitop3:0x36
	v_add_u32_e32 v133, 0, v86
	ds_read_b128 v[86:89], v85
	ds_read_b128 v[142:145], v133
	s_waitcnt lgkmcnt(1)
	v_mfma_f32_16x16x32_bf16 v[86:89], v[86:89], v[60:63], 0
	v_bitop3_b32 v85, v83, s77, v107 bitop3:0x36
	v_bitop3_b32 v83, v83, s77, v109 bitop3:0x36
	v_add_u32_e32 v85, 0, v85
	v_add_u32_e32 v83, 0, v83
	ds_read_b128 v[146:149], v85
	ds_read_b128 v[150:153], v83
	v_or_b32_e32 v83, v80, v101
	v_bfe_u32 v80, v80, 2, 2
	v_bitop3_b32 v85, v80, v99, v102 bitop3:0x36
	s_waitcnt lgkmcnt(2)
	v_mfma_f32_16x16x32_bf16 v[86:89], v[142:145], v[56:59], v[86:89]
	v_lshlrev_b32_e32 v83, 8, v83
	v_lshlrev_b32_e32 v85, 4, v85
	v_bitop3_b32 v133, v80, v104, v102 bitop3:0x36
	v_bitop3_b32 v85, v85, s77, v83 bitop3:0x36
	v_lshlrev_b32_e32 v133, 4, v133
	v_add_u32_e32 v85, 0, v85
	v_bitop3_b32 v133, v133, s77, v83 bitop3:0x36
	v_add_u32_e32 v133, 0, v133
	ds_read_b128 v[142:145], v85
	ds_read_b128 v[154:157], v133
	s_waitcnt lgkmcnt(3)
	v_mfma_f32_16x16x32_bf16 v[86:89], v[146:149], v[52:55], v[86:89]
	v_bitop3_b32 v85, v80, v106, v102 bitop3:0x36
	v_lshlrev_b32_e32 v85, 4, v85
	v_bitop3_b32 v85, v85, s77, v83 bitop3:0x36
	v_add_u32_e32 v85, 0, v85
	s_waitcnt lgkmcnt(2)
	v_mfma_f32_16x16x32_bf16 v[146:149], v[150:153], v[48:51], v[86:89]
	v_bitop3_b32 v80, v80, v108, v102 bitop3:0x36
	v_lshlrev_b32_e32 v80, 4, v80
	v_bitop3_b32 v80, v80, s77, v83 bitop3:0x36
	ds_read_b128 v[86:89], v85
	s_waitcnt lgkmcnt(2)
	v_mfma_f32_16x16x32_bf16 v[142:145], v[142:145], v[60:63], 0
	v_add_u32_e32 v80, 0, v80
	ds_read_b128 v[150:153], v80
	v_or_b32_e32 v80, s78, v100
	s_waitcnt lgkmcnt(2)
; #define LAS __attribute__((address_space(3)))
; __device__ __forceinline__ void attn_compute(LAS unsigned char* lds, const bf16x8 (&qf)[4], const AttnUnit& u, bf16* og, float* lse) {
;     ...
;             for (int s = 0; s < 4; ++s) a = __builtin_amdgcn_mfma_f32_16x16x32_bf16(kf[T][s], qf[s], a, 0, 0, 0);
;             sc[kk][T] = a;
;         }
;     }
;     float tb[5][2][4];
;     { const LAS float* tp = tab + (31 - 16 * (w & 1) - i15 + 8 * kg);
; #pragma unroll
;       for (int kk = 0; kk < 5; ++kk)
; #pragma unroll
;           for (int T = 0; T < 2; ++T)
; #pragma unroll
;               for (int jj = 0; jj < 4; ++jj) tb[kk][T][jj] = tp[32 * kk + 4 * T + jj]; }
;     const float SCL = 0.08838834764831845f * 1.4426950408889634f;
;     float mx = -1e30f;
; #pragma unroll
;     for (int kk = 0; kk < 5; ++kk) {
;         const bool dead = (n == 0) && (ks0 + kk < 4);
; #pragma unroll
;         for (int T = 0; T < 2; ++T)
; #pragma unroll
;             for (int jj = 0; jj < 4; ++jj) { float v = sc[kk][T][jj] * SCL + tb[kk][T][jj]; v = dead ? -1e30f : v; sc[kk][T][jj] = v; mx = fmaxf(mx, v); }
	v_mfma_f32_16x16x32_bf16 v[142:145], v[154:157], v[56:59], v[142:145]
	v_or_b32_e32 v83, v80, v101
	v_lshlrev_b32_e32 v83, 8, v83
	v_bitop3_b32 v85, v83, s77, v103 bitop3:0x36
	s_waitcnt lgkmcnt(1)
	v_mfma_f32_16x16x32_bf16 v[86:89], v[86:89], v[52:55], v[142:145]
	v_add_u32_e32 v85, 0, v85
	v_or_b32_e32 v80, 4, v80
	s_waitcnt lgkmcnt(0)
	v_mfma_f32_16x16x32_bf16 v[142:145], v[150:153], v[48:51], v[86:89]
	s_nop 3
	v_bitop3_b32 v86, v83, s77, v105 bitop3:0x36
	v_add_u32_e32 v133, 0, v86
	ds_read_b128 v[86:89], v85
	ds_read_b128 v[150:153], v133
	s_waitcnt lgkmcnt(1)
	v_mfma_f32_16x16x32_bf16 v[86:89], v[86:89], v[60:63], 0
	v_bitop3_b32 v85, v83, s77, v107 bitop3:0x36
	v_bitop3_b32 v83, v83, s77, v109 bitop3:0x36
	v_add_u32_e32 v85, 0, v85
	v_add_u32_e32 v83, 0, v83
	ds_read_b128 v[154:157], v85
	ds_read_b128 v[158:161], v83
	v_or_b32_e32 v83, v80, v101
	v_bfe_u32 v80, v80, 2, 2
	v_bitop3_b32 v85, v80, v99, v102 bitop3:0x36
	s_waitcnt lgkmcnt(2)
	v_mfma_f32_16x16x32_bf16 v[86:89], v[150:153], v[56:59], v[86:89]
	v_lshlrev_b32_e32 v83, 8, v83
	v_lshlrev_b32_e32 v85, 4, v85
	v_bitop3_b32 v133, v80, v104, v102 bitop3:0x36
	v_bitop3_b32 v85, v85, s77, v83 bitop3:0x36
	v_lshlrev_b32_e32 v133, 4, v133
	v_add_u32_e32 v85, 0, v85
	v_bitop3_b32 v133, v133, s77, v83 bitop3:0x36
	v_add_u32_e32 v133, 0, v133
	ds_read_b128 v[150:153], v85
	ds_read_b128 v[162:165], v133
	s_waitcnt lgkmcnt(3)
	v_mfma_f32_16x16x32_bf16 v[86:89], v[154:157], v[52:55], v[86:89]
	v_bitop3_b32 v85, v80, v106, v102 bitop3:0x36
	v_lshlrev_b32_e32 v85, 4, v85
	v_bitop3_b32 v85, v85, s77, v83 bitop3:0x36
	v_add_u32_e32 v85, 0, v85
	s_waitcnt lgkmcnt(2)
	v_mfma_f32_16x16x32_bf16 v[154:157], v[158:161], v[48:51], v[86:89]
	v_bitop3_b32 v80, v80, v108, v102 bitop3:0x36
	v_lshlrev_b32_e32 v80, 4, v80
	v_bitop3_b32 v80, v80, s77, v83 bitop3:0x36
	ds_read_b128 v[86:89], v85
	s_waitcnt lgkmcnt(2)
	v_mfma_f32_16x16x32_bf16 v[60:63], v[150:153], v[60:63], 0
	v_add_u32_e32 v80, 0, v80
	s_waitcnt lgkmcnt(1)
	v_mfma_f32_16x16x32_bf16 v[56:59], v[162:165], v[56:59], v[60:63]
	s_nop 4
	ds_read_b128 v[60:63], v80
	s_waitcnt lgkmcnt(1)
	v_mfma_f32_16x16x32_bf16 v[52:55], v[86:89], v[52:55], v[56:59]
	s_waitcnt lgkmcnt(0)
	v_mfma_f32_16x16x32_bf16 v[52:55], v[60:63], v[48:51], v[52:55]
	v_sub_u32_e32 v48, s30, v92
	v_lshl_add_u32 v48, v48, 2, v110
	s_cselect_b64 s[30:31], -1, 0
	s_cmpk_lt_u32 s85, 0x200
	ds_read2_b32 v[56:57], v48 offset0:15 offset1:16
	ds_read2_b32 v[58:59], v48 offset0:17 offset1:18
	ds_read2_b32 v[60:61], v48 offset0:19 offset1:20
	ds_read2_b32 v[62:63], v48 offset0:21 offset1:22
	ds_read2_b32 v[150:151], v48 offset0:47 offset1:48
	ds_read2_b32 v[152:153], v48 offset0:49 offset1:50
	ds_read2_b32 v[158:159], v48 offset0:51 offset1:52
	ds_read2_b32 v[160:161], v48 offset0:53 offset1:54
	ds_read2_b32 v[162:163], v48 offset0:79 offset1:80
	ds_read2_b32 v[164:165], v48 offset0:81 offset1:82
	ds_read2_b32 v[166:167], v48 offset0:83 offset1:84
	ds_read2_b32 v[168:169], v48 offset0:85 offset1:86
	ds_read2_b32 v[170:171], v48 offset0:111 offset1:112
	ds_read2_b32 v[172:173], v48 offset0:113 offset1:114
	ds_read2_b32 v[174:175], v48 offset0:115 offset1:116
	ds_read2_b32 v[176:177], v48 offset0:117 offset1:118
	ds_read2_b32 v[88:89], v48 offset0:143 offset1:144
	ds_read2_b32 v[86:87], v48 offset0:145 offset1:146
	ds_read2_b32 v[50:51], v48 offset0:147 offset1:148
	ds_read2_b32 v[48:49], v48 offset0:149 offset1:150
	s_cselect_b64 s[86:87], -1, 0
	s_waitcnt lgkmcnt(14)
	v_fmamk_f32 v56, v68, 0x3e0293ee, v56
	s_and_b64 vcc, s[30:31], s[86:87]
	v_fmac_f32_e32 v57, 0x3e0293ee, v69
	v_cndmask_b32_e32 v56, v56, v131, vcc
	v_cndmask_b32_e32 v57, v57, v131, vcc
	v_fmamk_f32 v58, v70, 0x3e0293ee, v58
	v_fmac_f32_e32 v59, 0x3e0293ee, v71
	v_max3_f32 v68, v56, s74, v57
	v_cndmask_b32_e32 v58, v58, v131, vcc
	v_cndmask_b32_e32 v59, v59, v131, vcc
	v_fmamk_f32 v60, v64, 0x3e0293ee, v60
	v_fmac_f32_e32 v61, 0x3e0293ee, v65
	s_cmpk_lt_u32 s85, 0x180
	v_max3_f32 v68, v68, v58, v59
	v_cndmask_b32_e32 v60, v60, v131, vcc
	v_cndmask_b32_e32 v61, v61, v131, vcc
	v_fmamk_f32 v62, v66, 0x3e0293ee, v62
	v_fmac_f32_e32 v63, 0x3e0293ee, v67
	s_cselect_b64 s[86:87], -1, 0
	v_max3_f32 v64, v68, v60, v61
	v_cndmask_b32_e32 v62, v62, v131, vcc
	v_cndmask_b32_e32 v63, v63, v131, vcc
	v_fmamk_f32 v65, v76, 0x3e0293ee, v150
	s_and_b64 vcc, s[30:31], s[86:87]
	v_fmac_f32_e32 v151, 0x3e0293ee, v77
	v_max3_f32 v64, v64, v62, v63
	v_cndmask_b32_e32 v69, v65, v131, vcc
	v_cndmask_b32_e32 v70, v151, v131, vcc
	v_fmamk_f32 v65, v78, 0x3e0293ee, v152
	v_fmac_f32_e32 v153, 0x3e0293ee, v79
	v_max3_f32 v64, v64, v69, v70
	v_cndmask_b32_e32 v71, v65, v131, vcc
	v_cndmask_b32_e32 v76, v153, v131, vcc
	s_waitcnt lgkmcnt(13)
	v_fmamk_f32 v65, v72, 0x3e0293ee, v158
	v_fmac_f32_e32 v159, 0x3e0293ee, v73
	s_cmpk_lt_u32 s85, 0x100
	v_max3_f32 v64, v64, v71, v76
	v_cndmask_b32_e32 v72, v65, v131, vcc
	v_cndmask_b32_e32 v73, v159, v131, vcc
	s_waitcnt lgkmcnt(12)
	v_fmamk_f32 v65, v74, 0x3e0293ee, v160
	v_fmac_f32_e32 v161, 0x3e0293ee, v75
	s_cselect_b64 s[86:87], -1, 0
	v_max3_f32 v64, v64, v72, v73
	v_cndmask_b32_e32 v74, v65, v131, vcc
	v_cndmask_b32_e32 v75, v161, v131, vcc
	s_waitcnt lgkmcnt(11)
	v_fmamk_f32 v65, v138, 0x3e0293ee, v162
	s_and_b64 vcc, s[30:31], s[86:87]
	v_fmac_f32_e32 v163, 0x3e0293ee, v139
	v_max3_f32 v64, v64, v74, v75
	v_cndmask_b32_e32 v77, v65, v131, vcc
	v_cndmask_b32_e32 v78, v163, v131, vcc
	s_waitcnt lgkmcnt(10)
	v_fmamk_f32 v65, v140, 0x3e0293ee, v164
	v_fmac_f32_e32 v165, 0x3e0293ee, v141
	v_max3_f32 v64, v64, v77, v78
	v_cndmask_b32_e32 v79, v65, v131, vcc
	v_cndmask_b32_e32 v83, v165, v131, vcc
	s_waitcnt lgkmcnt(9)
; __device__ __forceinline__ unsigned cvtpk(float lo, float hi) { f32x2_t v = {lo, hi}; bf16x2_t b = __builtin_convertvector(v, bf16x2_t); return __builtin_bit_cast(unsigned, b); }
; __device__ __forceinline__ void attn_compute(LAS unsigned char* lds, const bf16x8 (&qf)[4], const AttnUnit& u, bf16* og, float* lse) {
;     ...
; #pragma unroll
;     for (int kk = 0; kk < 5; ++kk) {
;         const bool dead = (n == 0) && (ks0 + kk < 4);
; #pragma unroll
;         for (int T = 0; T < 2; ++T)
; #pragma unroll
;             for (int jj = 0; jj < 4; ++jj) { float v = sc[kk][T][jj] * SCL + tb[kk][T][jj]; v = dead ? -1e30f : v; sc[kk][T][jj] = v; mx = fmaxf(mx, v); }
;     }
;     mx = fmaxf(mx, __shfl_xor(mx, 16)); mx = fmaxf(mx, __shfl_xor(mx, 32));
;     float l = 0.f;
;     bf16x8 pf[5];
; #pragma unroll
;     for (int kk = 0; kk < 5; ++kk) {
;         float e[8];
; #pragma unroll
;         for (int T = 0; T < 2; ++T)
; #pragma unroll
;             for (int jj = 0; jj < 4; ++jj) { const float p = __builtin_amdgcn_exp2f(sc[kk][T][jj] - mx); e[4 * T + jj] = p; l += p; }
;         v4u pw; pw.x = cvtpk(e[0], e[1]); pw.y = cvtpk(e[2], e[3]); pw.z = cvtpk(e[4], e[5]); pw.w = cvtpk(e[6], e[7]);
;         pf[kk] = __builtin_bit_cast(bf16x8, pw);
;     }
	v_fmamk_f32 v65, v134, 0x3e0293ee, v166
	v_fmac_f32_e32 v167, 0x3e0293ee, v135
	s_cmpk_lt_u32 s85, 0x80
	v_max3_f32 v64, v64, v79, v83
	v_cndmask_b32_e32 v85, v65, v131, vcc
	v_cndmask_b32_e32 v133, v167, v131, vcc
	s_waitcnt lgkmcnt(8)
	v_fmamk_f32 v65, v136, 0x3e0293ee, v168
	v_fmac_f32_e32 v169, 0x3e0293ee, v137
	s_cselect_b64 s[84:85], -1, 0
	v_max3_f32 v64, v64, v85, v133
	v_cndmask_b32_e32 v134, v65, v131, vcc
	v_cndmask_b32_e32 v135, v169, v131, vcc
	s_waitcnt lgkmcnt(7)
	v_fmamk_f32 v65, v146, 0x3e0293ee, v170
	s_and_b64 vcc, s[30:31], s[84:85]
	v_fmac_f32_e32 v171, 0x3e0293ee, v147
	v_max3_f32 v64, v64, v134, v135
	v_cndmask_b32_e32 v136, v65, v131, vcc
	v_cndmask_b32_e32 v137, v171, v131, vcc
	s_waitcnt lgkmcnt(6)
	v_fmamk_f32 v65, v148, 0x3e0293ee, v172
	v_fmac_f32_e32 v173, 0x3e0293ee, v149
	v_max3_f32 v64, v64, v136, v137
	v_cndmask_b32_e32 v138, v65, v131, vcc
	v_cndmask_b32_e32 v139, v173, v131, vcc
	s_waitcnt lgkmcnt(5)
	v_fmamk_f32 v65, v142, 0x3e0293ee, v174
	v_fmac_f32_e32 v175, 0x3e0293ee, v143
	v_max3_f32 v64, v64, v138, v139
	v_cndmask_b32_e32 v140, v65, v131, vcc
	v_cndmask_b32_e32 v141, v175, v131, vcc
	s_waitcnt lgkmcnt(4)
	v_fmamk_f32 v65, v144, 0x3e0293ee, v176
	v_fmac_f32_e32 v177, 0x3e0293ee, v145
	v_max3_f32 v64, v64, v140, v141
	v_cndmask_b32_e32 v142, v65, v131, vcc
	v_cndmask_b32_e32 v143, v177, v131, vcc
	v_max3_f32 v64, v64, v142, v143
	s_waitcnt lgkmcnt(3)
	v_fmamk_f32 v88, v154, 0x3e0293ee, v88
	v_fmac_f32_e32 v89, 0x3e0293ee, v155
	s_waitcnt lgkmcnt(0)
	v_fmamk_f32 v48, v54, 0x3e0293ee, v48
	v_and_b32_e32 v54, 64, v132
	v_max3_f32 v64, v64, v88, v89
	v_fmamk_f32 v86, v156, 0x3e0293ee, v86
	v_fmac_f32_e32 v87, 0x3e0293ee, v157
	v_fmac_f32_e32 v51, 0x3e0293ee, v53
	v_xor_b32_e32 v53, 16, v132
	v_add_u32_e32 v54, 64, v54
	v_max3_f32 v64, v64, v86, v87
	v_fmamk_f32 v50, v52, 0x3e0293ee, v50
	v_cmp_lt_i32_e32 vcc, v53, v54
	v_max3_f32 v52, v64, v50, v51
	v_fmac_f32_e32 v49, 0x3e0293ee, v55
	v_cndmask_b32_e32 v53, v132, v53, vcc
	v_max3_f32 v52, v52, v48, v49
	v_lshlrev_b32_e32 v144, 2, v53
	ds_bpermute_b32 v53, v144, v52
	s_or_b32 s62, s62, s11
	s_waitcnt lgkmcnt(0)
	v_max_f32_e32 v53, v53, v53
	v_max_f32_e32 v52, v52, v53
	v_xor_b32_e32 v53, 32, v132
	v_cmp_lt_i32_e32 vcc, v53, v54
	v_or_b32_e32 v54, s81, v92
	v_add_u32_e32 v80, s54, v54
	v_cndmask_b32_e32 v53, v132, v53, vcc
	v_lshlrev_b32_e32 v145, 2, v53
	ds_bpermute_b32 v53, v145, v52
	s_waitcnt lgkmcnt(0)
	v_max_f32_e32 v53, v53, v53
	v_max_f32_e32 v68, v52, v53
	v_sub_f32_e32 v52, v56, v68
	v_exp_f32_e32 v52, v52
	v_sub_f32_e32 v53, v57, v68
	v_exp_f32_e32 v53, v53
	v_sub_f32_e32 v54, v58, v68
	v_exp_f32_e32 v54, v54
	v_sub_f32_e32 v55, v59, v68
	v_exp_f32_e32 v55, v55
	v_sub_f32_e32 v57, v60, v68
	v_add_f32_e32 v56, 0, v52
	v_exp_f32_e32 v57, v57
	v_sub_f32_e32 v58, v61, v68
	v_add_f32_e32 v56, v53, v56
	v_exp_f32_e32 v58, v58
	v_sub_f32_e32 v59, v62, v68
	v_add_f32_e32 v56, v54, v56
	v_exp_f32_e32 v59, v59
	v_sub_f32_e32 v60, v63, v68
	v_add_f32_e32 v56, v55, v56
	v_exp_f32_e32 v60, v60
	v_cvt_pk_bf16_f32 v64, v52, v53
	v_sub_f32_e32 v52, v69, v68
	v_add_f32_e32 v56, v57, v56
	v_exp_f32_e32 v52, v52
	v_sub_f32_e32 v53, v70, v68
	v_add_f32_e32 v56, v58, v56
	v_cvt_pk_bf16_f32 v65, v54, v55
	v_exp_f32_e32 v53, v53
	v_sub_f32_e32 v54, v71, v68
	v_add_f32_e32 v56, v59, v56
	v_exp_f32_e32 v54, v54
	v_sub_f32_e32 v55, v76, v68
	v_add_f32_e32 v56, v60, v56
	v_cvt_pk_bf16_f32 v66, v57, v58
	v_exp_f32_e32 v55, v55
	v_sub_f32_e32 v57, v72, v68
	v_add_f32_e32 v56, v52, v56
	v_exp_f32_e32 v57, v57
	v_sub_f32_e32 v58, v73, v68
	v_cvt_pk_bf16_f32 v67, v59, v60
	v_add_f32_e32 v56, v53, v56
	v_exp_f32_e32 v58, v58
	v_sub_f32_e32 v59, v74, v68
	v_add_f32_e32 v56, v54, v56
	v_exp_f32_e32 v59, v59
	v_sub_f32_e32 v60, v75, v68
	v_add_f32_e32 v56, v55, v56
	v_exp_f32_e32 v63, v60
	v_cvt_pk_bf16_f32 v60, v52, v53
	v_sub_f32_e32 v52, v77, v68
	v_add_f32_e32 v56, v57, v56
	v_exp_f32_e32 v52, v52
	v_sub_f32_e32 v53, v78, v68
	v_add_f32_e32 v56, v58, v56
	v_cvt_pk_bf16_f32 v61, v54, v55
	v_exp_f32_e32 v53, v53
	v_sub_f32_e32 v54, v79, v68
	v_add_f32_e32 v56, v59, v56
	v_exp_f32_e32 v54, v54
	v_sub_f32_e32 v55, v83, v68
	v_add_f32_e32 v56, v63, v56
	v_cvt_pk_bf16_f32 v62, v57, v58
	v_exp_f32_e32 v55, v55
	v_sub_f32_e32 v57, v85, v68
	v_add_f32_e32 v56, v52, v56
	v_exp_f32_e32 v58, v57
	v_sub_f32_e32 v57, v133, v68
	v_cvt_pk_bf16_f32 v63, v59, v63
	v_add_f32_e32 v56, v53, v56
	v_exp_f32_e32 v59, v57
	v_sub_f32_e32 v57, v134, v68
	v_add_f32_e32 v56, v54, v56
	v_exp_f32_e32 v69, v57
	v_sub_f32_e32 v57, v135, v68
	v_add_f32_e32 v56, v55, v56
	v_exp_f32_e32 v70, v57
	v_add_f32_e32 v56, v58, v56
	v_add_f32_e32 v56, v59, v56
	v_add_f32_e32 v56, v69, v56
	v_add_f32_e32 v71, v70, v56
	v_cvt_pk_bf16_f32 v56, v52, v53
	v_sub_f32_e32 v52, v136, v68
	v_exp_f32_e32 v52, v52
	v_sub_f32_e32 v53, v137, v68
	v_cvt_pk_bf16_f32 v57, v54, v55
	v_exp_f32_e32 v53, v53
	v_sub_f32_e32 v54, v138, v68
	v_exp_f32_e32 v54, v54
	v_sub_f32_e32 v55, v139, v68
	v_cvt_pk_bf16_f32 v58, v58, v59
	v_cvt_pk_bf16_f32 v59, v69, v70
	v_exp_f32_e32 v55, v55
	v_add_f32_e32 v69, v52, v71
	v_sub_f32_e32 v70, v140, v68
	v_sub_f32_e32 v71, v141, v68
	v_exp_f32_e32 v70, v70
	v_exp_f32_e32 v71, v71
	v_add_f32_e32 v69, v53, v69
	v_sub_f32_e32 v72, v142, v68
	v_sub_f32_e32 v73, v143, v68
	v_add_f32_e32 v69, v54, v69
	v_exp_f32_e32 v72, v72
	v_exp_f32_e32 v73, v73
	v_add_f32_e32 v69, v55, v69
	v_add_f32_e32 v69, v70, v69
	v_cvt_pk_bf16_f32 v52, v52, v53
	v_cvt_pk_bf16_f32 v53, v54, v55
	v_cvt_pk_bf16_f32 v54, v70, v71
	v_sub_f32_e32 v70, v88, v68
	v_add_f32_e32 v69, v71, v69
	v_exp_f32_e32 v70, v70
	v_sub_f32_e32 v71, v89, v68
; __device__ __forceinline__ unsigned cvtpk(float lo, float hi) { f32x2_t v = {lo, hi}; bf16x2_t b = __builtin_convertvector(v, bf16x2_t); return __builtin_bit_cast(unsigned, b); }
; #define ATT_VLOAD(kk_, buf_) do { const unsigned r0_ = 32 * (ks0 + (kk_)) + 8 * kg + q4; _Pragma("unroll") for (int c = 0; c < 8; ++c) { \
;         vlo[buf_][c] = vtr(vbase + ((off_b(r0_, 2 * c + (p4 >> 1)) + 8 * (p4 & 1)) ^ par)); vhi[buf_][c] = vtr(vbase + ((off_b(r0_ + 4, 2 * c + (p4 >> 1)) + 8 * (p4 & 1)) ^ par)); } } while (0)
; __device__ __forceinline__ void attn_compute(LAS unsigned char* lds, const bf16x8 (&qf)[4], const AttnUnit& u, bf16* og, float* lse) {
;     ...
;     float l = 0.f;
;     bf16x8 pf[5];
; #pragma unroll
;     for (int kk = 0; kk < 5; ++kk) {
;         float e[8];
; #pragma unroll
;         for (int T = 0; T < 2; ++T)
; #pragma unroll
;             for (int jj = 0; jj < 4; ++jj) { const float p = __builtin_amdgcn_exp2f(sc[kk][T][jj] - mx); e[4 * T + jj] = p; l += p; }
;         v4u pw; pw.x = cvtpk(e[0], e[1]); pw.y = cvtpk(e[2], e[3]); pw.z = cvtpk(e[4], e[5]); pw.w = cvtpk(e[6], e[7]);
;         pf[kk] = __builtin_bit_cast(bf16x8, pw);
;     }
;     l += __shfl_xor(l, 16); l += __shfl_xor(l, 32);
;     f32x4 o[8];
; #pragma unroll
;     for (int c = 0; c < 8; ++c) o[c] = (f32x4){0.f, 0.f, 0.f, 0.f};
;     const unsigned vbase = (unsigned)(uintptr_t)Vs;
;     const unsigned q4 = (lane & 15) >> 2, p4 = lane & 3;
;     s16x4 vlo[2][8], vhi[2][8];
;     ...
;     ATT_VLOAD(0, 0);
; #pragma unroll
;     for (int kk = 0; kk < 5; ++kk) {
;         if (kk < 4) ATT_VLOAD(kk + 1, (kk + 1) & 1);
; #pragma unroll
;         for (int c = 0; c < 8; ++c) {
;             const s16x4 lo = vlo[kk & 1][c], hi = vhi[kk & 1][c];
;             const bf16x8 vf = (bf16x8){lo[0], lo[1], lo[2], lo[3], hi[0], hi[1], hi[2], hi[3]};
;             o[c] = __builtin_amdgcn_mfma_f32_16x16x32_bf16(vf, pf[kk], o[c], 0, 0, 0);
;         }
;     }
	v_add_f32_e32 v69, v72, v69
	v_cvt_pk_bf16_f32 v55, v72, v73
	v_exp_f32_e32 v71, v71
	v_sub_f32_e32 v72, v86, v68
	v_add_f32_e32 v69, v73, v69
	v_exp_f32_e32 v72, v72
	v_sub_f32_e32 v73, v87, v68
	v_exp_f32_e32 v73, v73
	v_sub_f32_e32 v50, v50, v68
	v_add_f32_e32 v69, v70, v69
	v_exp_f32_e32 v50, v50
	v_sub_f32_e32 v51, v51, v68
	v_add_f32_e32 v69, v71, v69
	v_exp_f32_e32 v51, v51
	v_sub_f32_e32 v48, v48, v68
	v_add_f32_e32 v69, v72, v69
	v_exp_f32_e32 v74, v48
	v_sub_f32_e32 v48, v49, v68
	v_add_f32_e32 v69, v73, v69
	v_exp_f32_e32 v75, v48
	v_add_f32_e32 v48, v50, v69
	v_add_f32_e32 v48, v51, v48
	v_add_f32_e32 v48, v74, v48
	v_add_f32_e32 v69, v75, v48
	v_cvt_pk_bf16_f32 v48, v70, v71
	v_or_b32_e32 v71, s83, v111
	v_lshl_or_b32 v83, v71, 8, v114
	v_or_b32_e32 v71, 4, v71
	v_bitop3_b32 v133, v83, s77, v121 bitop3:0x36
	v_bfe_u32 v85, v71, 2, 2
	v_add_u32_e32 v133, s73, v133
	ds_read_b64_tr_b16 v[134:135], v133
	v_bitop3_b32 v133, v85, v120, v113 bitop3:0x36
	v_lshl_or_b32 v71, v71, 8, v114
	v_lshlrev_b32_e32 v133, 4, v133
	v_bitop3_b32 v133, v133, s77, v71 bitop3:0x36
	v_add_u32_e32 v133, s73, v133
	ds_read_b64_tr_b16 v[136:137], v133
	v_bitop3_b32 v133, v83, s77, v123 bitop3:0x36
	v_add_u32_e32 v133, s73, v133
	ds_read_b64_tr_b16 v[138:139], v133
	v_bitop3_b32 v133, v85, v122, v113 bitop3:0x36
	v_lshlrev_b32_e32 v133, 4, v133
	v_bitop3_b32 v133, v133, s77, v71 bitop3:0x36
	v_add_u32_e32 v133, s73, v133
	ds_bpermute_b32 v76, v144, v69
	ds_read_b64_tr_b16 v[140:141], v133
	v_bitop3_b32 v133, v83, s77, v126 bitop3:0x36
	v_add_u32_e32 v133, s73, v133
	ds_read_b64_tr_b16 v[142:143], v133
	v_bitop3_b32 v133, v85, v124, v113 bitop3:0x36
	v_lshlrev_b32_e32 v133, 4, v133
	v_bitop3_b32 v133, v133, s77, v71 bitop3:0x36
	s_waitcnt lgkmcnt(2)
	v_add_f32_e32 v69, v69, v76
	v_add_u32_e32 v133, s73, v133
	v_cvt_pk_bf16_f32 v49, v72, v73
	ds_bpermute_b32 v70, v145, v69
	v_bitop3_b32 v72, v83, s77, v115 bitop3:0x36
	v_bitop3_b32 v76, v83, s77, v117 bitop3:0x36
	v_bitop3_b32 v86, v83, s77, v119 bitop3:0x36
	ds_read_b64_tr_b16 v[144:145], v133
	v_bitop3_b32 v133, v83, s77, v128 bitop3:0x36
	v_bitop3_b32 v83, v83, s77, v130 bitop3:0x36
	v_add_u32_e32 v133, s73, v133
	v_add_u32_e32 v83, s73, v83
	v_cvt_pk_bf16_f32 v50, v50, v51
	v_cvt_pk_bf16_f32 v51, v74, v75
	v_bitop3_b32 v74, v85, v112, v113 bitop3:0x36
	v_bitop3_b32 v78, v85, v116, v113 bitop3:0x36
	v_bitop3_b32 v88, v85, v118, v113 bitop3:0x36
	ds_read_b64_tr_b16 v[146:147], v133
	v_bitop3_b32 v133, v85, v127, v113 bitop3:0x36
	ds_read_b64_tr_b16 v[150:151], v83
	v_bitop3_b32 v83, v85, v129, v113 bitop3:0x36
	v_lshlrev_b32_e32 v74, 4, v74
	v_lshlrev_b32_e32 v78, 4, v78
	v_lshlrev_b32_e32 v88, 4, v88
	v_lshlrev_b32_e32 v133, 4, v133
	v_lshlrev_b32_e32 v83, 4, v83
	v_bitop3_b32 v74, v74, s77, v71 bitop3:0x36
	v_bitop3_b32 v78, v78, s77, v71 bitop3:0x36
	v_bitop3_b32 v88, v88, s77, v71 bitop3:0x36
	v_bitop3_b32 v133, v133, s77, v71 bitop3:0x36
	v_bitop3_b32 v71, v83, s77, v71 bitop3:0x36
	v_add_u32_e32 v71, s73, v71
	ds_read_b64_tr_b16 v[152:153], v71
	v_or_b32_e32 v71, s82, v111
	v_add_u32_e32 v133, s73, v133
	v_lshl_or_b32 v83, v71, 8, v114
	ds_read_b64_tr_b16 v[148:149], v133
	v_or_b32_e32 v71, 4, v71
	v_bitop3_b32 v133, v83, s77, v115 bitop3:0x36
	v_bfe_u32 v85, v71, 2, 2
	v_add_u32_e32 v133, s73, v133
	ds_read_b64_tr_b16 v[154:155], v133
	v_bitop3_b32 v133, v85, v112, v113 bitop3:0x36
	v_lshl_or_b32 v71, v71, 8, v114
	v_lshlrev_b32_e32 v133, 4, v133
	v_bitop3_b32 v133, v133, s77, v71 bitop3:0x36
	v_add_u32_e32 v133, s73, v133
	ds_read_b64_tr_b16 v[156:157], v133
	v_bitop3_b32 v133, v83, s77, v117 bitop3:0x36
	v_add_u32_e32 v133, s73, v133
	ds_read_b64_tr_b16 v[158:159], v133
	v_bitop3_b32 v133, v85, v116, v113 bitop3:0x36
	v_lshlrev_b32_e32 v133, 4, v133
	v_bitop3_b32 v133, v133, s77, v71 bitop3:0x36
	v_add_u32_e32 v133, s73, v133
	ds_read_b64_tr_b16 v[160:161], v133
	v_bitop3_b32 v133, v83, s77, v119 bitop3:0x36
	v_add_u32_e32 v133, s73, v133
	ds_read_b64_tr_b16 v[162:163], v133
	v_bitop3_b32 v133, v85, v118, v113 bitop3:0x36
	v_lshlrev_b32_e32 v133, 4, v133
	v_bitop3_b32 v133, v133, s77, v71 bitop3:0x36
	v_add_u32_e32 v133, s73, v133
	ds_read_b64_tr_b16 v[164:165], v133
	v_bitop3_b32 v133, v83, s77, v121 bitop3:0x36
	v_add_u32_e32 v133, s73, v133
	ds_read_b64_tr_b16 v[166:167], v133
	v_bitop3_b32 v133, v85, v120, v113 bitop3:0x36
	v_lshlrev_b32_e32 v133, 4, v133
	v_bitop3_b32 v133, v133, s77, v71 bitop3:0x36
	v_add_u32_e32 v133, s73, v133
	ds_read_b64_tr_b16 v[168:169], v133
	v_bitop3_b32 v133, v83, s77, v123 bitop3:0x36
	v_add_u32_e32 v133, s73, v133
	ds_read_b64_tr_b16 v[170:171], v133
	v_bitop3_b32 v133, v85, v122, v113 bitop3:0x36
	v_lshlrev_b32_e32 v133, 4, v133
	v_bitop3_b32 v133, v133, s77, v71 bitop3:0x36
	v_add_u32_e32 v133, s73, v133
	ds_read_b64_tr_b16 v[172:173], v133
	v_bitop3_b32 v133, v83, s77, v126 bitop3:0x36
	v_add_u32_e32 v133, s73, v133
	ds_read_b64_tr_b16 v[174:175], v133
	v_bitop3_b32 v133, v85, v124, v113 bitop3:0x36
	v_lshlrev_b32_e32 v133, 4, v133
	v_bitop3_b32 v133, v133, s77, v71 bitop3:0x36
	v_add_u32_e32 v133, s73, v133
	v_add_u32_e32 v72, s73, v72
	v_add_u32_e32 v74, s73, v74
	v_add_u32_e32 v76, s73, v76
	v_add_u32_e32 v78, s73, v78
	v_add_u32_e32 v86, s73, v86
	v_add_u32_e32 v88, s73, v88
	ds_read_b64_tr_b16 v[176:177], v133
	v_bitop3_b32 v133, v83, s77, v128 bitop3:0x36
	v_bitop3_b32 v83, v83, s77, v130 bitop3:0x36
	ds_read_b64_tr_b16 v[72:73], v72
	ds_read_b64_tr_b16 v[74:75], v74
	ds_read_b64_tr_b16 v[76:77], v76
	ds_read_b64_tr_b16 v[78:79], v78
	ds_read_b64_tr_b16 v[86:87], v86
	ds_read_b64_tr_b16 v[88:89], v88
	v_add_u32_e32 v133, s73, v133
	v_add_u32_e32 v83, s73, v83
	ds_read_b64_tr_b16 v[180:181], v133
	v_bitop3_b32 v133, v85, v127, v113 bitop3:0x36
	ds_read_b64_tr_b16 v[184:185], v83
	v_bitop3_b32 v83, v85, v129, v113 bitop3:0x36
	v_lshlrev_b32_e32 v133, 4, v133
	v_lshlrev_b32_e32 v83, 4, v83
	v_bitop3_b32 v133, v133, s77, v71 bitop3:0x36
	v_bitop3_b32 v71, v83, s77, v71 bitop3:0x36
	v_add_u32_e32 v71, s73, v71
	ds_read_b64_tr_b16 v[186:187], v71
	v_or_b32_e32 v71, s80, v111
	v_add_u32_e32 v133, s73, v133
	v_lshl_or_b32 v83, v71, 8, v114
	ds_read_b64_tr_b16 v[182:183], v133
	v_or_b32_e32 v71, 4, v71
	v_bitop3_b32 v133, v83, s77, v115 bitop3:0x36
	v_bfe_u32 v85, v71, 2, 2
	v_add_u32_e32 v133, s73, v133
	s_waitcnt lgkmcnt(8)
; #define ATT_VLOAD(kk_, buf_) do { const unsigned r0_ = 32 * (ks0 + (kk_)) + 8 * kg + q4; _Pragma("unroll") for (int c = 0; c < 8; ++c) { \
;         vlo[buf_][c] = vtr(vbase + ((off_b(r0_, 2 * c + (p4 >> 1)) + 8 * (p4 & 1)) ^ par)); vhi[buf_][c] = vtr(vbase + ((off_b(r0_ + 4, 2 * c + (p4 >> 1)) + 8 * (p4 & 1)) ^ par)); } } while (0)
; __device__ __forceinline__ void attn_compute(LAS unsigned char* lds, const bf16x8 (&qf)[4], const AttnUnit& u, bf16* og, float* lse) {
;     ...
;     ATT_VLOAD(0, 0);
; #pragma unroll
;     for (int kk = 0; kk < 5; ++kk) {
;         if (kk < 4) ATT_VLOAD(kk + 1, (kk + 1) & 1);
; #pragma unroll
;         for (int c = 0; c < 8; ++c) {
;             const s16x4 lo = vlo[kk & 1][c], hi = vhi[kk & 1][c];
;             const bf16x8 vf = (bf16x8){lo[0], lo[1], lo[2], lo[3], hi[0], hi[1], hi[2], hi[3]};
;             o[c] = __builtin_amdgcn_mfma_f32_16x16x32_bf16(vf, pf[kk], o[c], 0, 0, 0);
;         }
;     }
	v_mfma_f32_16x16x32_bf16 v[72:75], v[72:75], v[64:67], 0
	v_lshl_or_b32 v71, v71, 8, v114
	s_waitcnt lgkmcnt(6)
	v_mfma_f32_16x16x32_bf16 v[76:79], v[76:79], v[64:67], 0
	s_waitcnt lgkmcnt(4)
	v_mfma_f32_16x16x32_bf16 v[86:89], v[86:89], v[64:67], 0
	v_mfma_f32_16x16x32_bf16 v[134:137], v[134:137], v[64:67], 0
	v_mfma_f32_16x16x32_bf16 v[138:141], v[138:141], v[64:67], 0
	v_mfma_f32_16x16x32_bf16 v[142:145], v[142:145], v[64:67], 0
	v_mfma_f32_16x16x32_bf16 v[146:149], v[146:149], v[64:67], 0
	v_mfma_f32_16x16x32_bf16 v[64:67], v[150:153], v[64:67], 0
	ds_read_b64_tr_b16 v[150:151], v133
	v_bitop3_b32 v133, v85, v112, v113 bitop3:0x36
	v_lshlrev_b32_e32 v133, 4, v133
	v_bitop3_b32 v133, v133, s77, v71 bitop3:0x36
	v_add_u32_e32 v133, s73, v133
	ds_read_b64_tr_b16 v[152:153], v133
	v_bitop3_b32 v133, v83, s77, v117 bitop3:0x36
	v_add_u32_e32 v133, s73, v133
	ds_read_b64_tr_b16 v[188:189], v133
	v_bitop3_b32 v133, v85, v116, v113 bitop3:0x36
	v_lshlrev_b32_e32 v133, 4, v133
	v_bitop3_b32 v133, v133, s77, v71 bitop3:0x36
	v_add_u32_e32 v133, s73, v133
	ds_read_b64_tr_b16 v[190:191], v133
	v_bitop3_b32 v133, v83, s77, v119 bitop3:0x36
	v_add_u32_e32 v133, s73, v133
	ds_read_b64_tr_b16 v[192:193], v133
	v_bitop3_b32 v133, v85, v118, v113 bitop3:0x36
	v_lshlrev_b32_e32 v133, 4, v133
	v_bitop3_b32 v133, v133, s77, v71 bitop3:0x36
	v_add_u32_e32 v133, s73, v133
	ds_read_b64_tr_b16 v[194:195], v133
	v_bitop3_b32 v133, v83, s77, v121 bitop3:0x36
	v_add_u32_e32 v133, s73, v133
	ds_read_b64_tr_b16 v[196:197], v133
	v_bitop3_b32 v133, v85, v120, v113 bitop3:0x36
	v_lshlrev_b32_e32 v133, 4, v133
	v_bitop3_b32 v133, v133, s77, v71 bitop3:0x36
	v_add_u32_e32 v133, s73, v133
	ds_read_b64_tr_b16 v[198:199], v133
	v_bitop3_b32 v133, v83, s77, v123 bitop3:0x36
	v_add_u32_e32 v133, s73, v133
	ds_read_b64_tr_b16 v[200:201], v133
	v_bitop3_b32 v133, v85, v122, v113 bitop3:0x36
	v_lshlrev_b32_e32 v133, 4, v133
	v_bitop3_b32 v133, v133, s77, v71 bitop3:0x36
	v_add_u32_e32 v133, s73, v133
	ds_read_b64_tr_b16 v[202:203], v133
	v_bitop3_b32 v133, v83, s77, v126 bitop3:0x36
	v_add_u32_e32 v133, s73, v133
	ds_read_b64_tr_b16 v[204:205], v133
	v_bitop3_b32 v133, v85, v124, v113 bitop3:0x36
	v_lshlrev_b32_e32 v133, 4, v133
	v_bitop3_b32 v133, v133, s77, v71 bitop3:0x36
	v_add_u32_e32 v133, s73, v133
	ds_read_b64_tr_b16 v[206:207], v133
	v_bitop3_b32 v133, v83, s77, v128 bitop3:0x36
	v_bitop3_b32 v83, v83, s77, v130 bitop3:0x36
	v_add_u32_e32 v133, s73, v133
	v_add_u32_e32 v83, s73, v83
	v_mfma_f32_16x16x32_bf16 v[72:75], v[154:157], v[60:63], v[72:75]
	ds_read_b64_tr_b16 v[154:155], v133
	v_bitop3_b32 v133, v85, v127, v113 bitop3:0x36
	v_lshlrev_b32_e32 v133, 4, v133
	v_mfma_f32_16x16x32_bf16 v[76:79], v[158:161], v[60:63], v[76:79]
	ds_read_b64_tr_b16 v[158:159], v83
	v_bitop3_b32 v83, v85, v129, v113 bitop3:0x36
	v_lshlrev_b32_e32 v83, 4, v83
	v_bitop3_b32 v133, v133, s77, v71 bitop3:0x36
	v_bitop3_b32 v71, v83, s77, v71 bitop3:0x36
	v_mfma_f32_16x16x32_bf16 v[86:89], v[162:165], v[60:63], v[86:89]
	v_add_u32_e32 v71, s73, v71
	v_add_u32_e32 v133, s73, v133
	ds_read_b64_tr_b16 v[160:161], v71
	v_mfma_f32_16x16x32_bf16 v[134:137], v[166:169], v[60:63], v[134:137]
	ds_read_b64_tr_b16 v[156:157], v133
	v_mfma_f32_16x16x32_bf16 v[138:141], v[170:173], v[60:63], v[138:141]
	v_mfma_f32_16x16x32_bf16 v[142:145], v[174:177], v[60:63], v[142:145]
	s_waitcnt lgkmcnt(14)
	v_mfma_f32_16x16x32_bf16 v[146:149], v[180:183], v[60:63], v[146:149]
	v_mfma_f32_16x16x32_bf16 v[60:63], v[184:187], v[60:63], v[64:67]
	s_nop 2
	v_or_b32_e32 v64, s79, v111
	v_lshl_or_b32 v71, v64, 8, v114
	v_or_b32_e32 v64, 4, v64
	v_bitop3_b32 v133, v71, s77, v117 bitop3:0x36
	v_bfe_u32 v83, v64, 2, 2
	v_add_u32_e32 v133, s73, v133
	ds_read_b64_tr_b16 v[162:163], v133
	v_bitop3_b32 v133, v83, v116, v113 bitop3:0x36
	v_lshl_or_b32 v85, v64, 8, v114
	v_lshlrev_b32_e32 v133, 4, v133
	v_bitop3_b32 v133, v133, s77, v85 bitop3:0x36
	v_add_u32_e32 v133, s73, v133
	ds_read_b64_tr_b16 v[164:165], v133
	v_bitop3_b32 v133, v71, s77, v119 bitop3:0x36
	v_add_u32_e32 v133, s73, v133
	ds_read_b64_tr_b16 v[166:167], v133
	v_bitop3_b32 v133, v83, v118, v113 bitop3:0x36
	v_lshlrev_b32_e32 v133, 4, v133
	v_bitop3_b32 v133, v133, s77, v85 bitop3:0x36
	v_add_u32_e32 v133, s73, v133
	ds_read_b64_tr_b16 v[168:169], v133
	v_bitop3_b32 v133, v71, s77, v121 bitop3:0x36
	v_add_u32_e32 v133, s73, v133
	ds_read_b64_tr_b16 v[170:171], v133
	v_bitop3_b32 v133, v83, v120, v113 bitop3:0x36
	v_lshlrev_b32_e32 v133, 4, v133
	v_bitop3_b32 v133, v133, s77, v85 bitop3:0x36
	v_add_u32_e32 v133, s73, v133
	ds_read_b64_tr_b16 v[172:173], v133
	v_bitop3_b32 v133, v71, s77, v123 bitop3:0x36
	v_add_u32_e32 v133, s73, v133
	ds_read_b64_tr_b16 v[174:175], v133
	v_bitop3_b32 v133, v83, v122, v113 bitop3:0x36
	v_lshlrev_b32_e32 v133, 4, v133
	v_bitop3_b32 v133, v133, s77, v85 bitop3:0x36
	v_add_u32_e32 v133, s73, v133
	ds_read_b64_tr_b16 v[176:177], v133
	v_bitop3_b32 v133, v71, s77, v126 bitop3:0x36
	v_add_u32_e32 v133, s73, v133
	ds_read_b64_tr_b16 v[180:181], v133
	v_bitop3_b32 v133, v83, v124, v113 bitop3:0x36
	v_lshlrev_b32_e32 v133, 4, v133
	v_bitop3_b32 v133, v133, s77, v85 bitop3:0x36
	v_add_u32_e32 v133, s73, v133
	v_bitop3_b32 v64, v71, s77, v115 bitop3:0x36
	ds_read_b64_tr_b16 v[182:183], v133
	v_bitop3_b32 v133, v71, s77, v128 bitop3:0x36
	v_bitop3_b32 v71, v71, s77, v130 bitop3:0x36
	v_add_u32_e32 v71, s73, v71
	v_add_u32_e32 v133, s73, v133
	ds_read_b64_tr_b16 v[184:185], v71
	v_bitop3_b32 v71, v83, v129, v113 bitop3:0x36
	v_mfma_f32_16x16x32_bf16 v[72:75], v[150:153], v[56:59], v[72:75]
	ds_read_b64_tr_b16 v[150:151], v133
	v_bitop3_b32 v133, v83, v127, v113 bitop3:0x36
	v_lshlrev_b32_e32 v71, 4, v71
	v_lshlrev_b32_e32 v133, 4, v133
	v_bitop3_b32 v71, v71, s77, v85 bitop3:0x36
	v_bitop3_b32 v66, v83, v112, v113 bitop3:0x36
	s_waitcnt lgkmcnt(14)
; #define ATT_VLOAD(kk_, buf_) do { const unsigned r0_ = 32 * (ks0 + (kk_)) + 8 * kg + q4; _Pragma("unroll") for (int c = 0; c < 8; ++c) { \
;         vlo[buf_][c] = vtr(vbase + ((off_b(r0_, 2 * c + (p4 >> 1)) + 8 * (p4 & 1)) ^ par)); vhi[buf_][c] = vtr(vbase + ((off_b(r0_ + 4, 2 * c + (p4 >> 1)) + 8 * (p4 & 1)) ^ par)); } } while (0)
; __device__ __forceinline__ void attn_compute(LAS unsigned char* lds, const bf16x8 (&qf)[4], const AttnUnit& u, bf16* og, float* lse) {
;     ...
;     ATT_VLOAD(0, 0);
; #pragma unroll
;     for (int kk = 0; kk < 5; ++kk) {
;         if (kk < 4) ATT_VLOAD(kk + 1, (kk + 1) & 1);
; #pragma unroll
;         for (int c = 0; c < 8; ++c) {
;             const s16x4 lo = vlo[kk & 1][c], hi = vhi[kk & 1][c];
;             const bf16x8 vf = (bf16x8){lo[0], lo[1], lo[2], lo[3], hi[0], hi[1], hi[2], hi[3]};
;             o[c] = __builtin_amdgcn_mfma_f32_16x16x32_bf16(vf, pf[kk], o[c], 0, 0, 0);
;         }
;     }
	v_mfma_f32_16x16x32_bf16 v[76:79], v[188:191], v[56:59], v[76:79]
	v_bitop3_b32 v133, v133, s77, v85 bitop3:0x36
	v_add_u32_e32 v71, s73, v71
	v_lshlrev_b32_e32 v66, 4, v66
	v_mfma_f32_16x16x32_bf16 v[86:89], v[192:195], v[56:59], v[86:89]
	v_add_u32_e32 v133, s73, v133
	ds_read_b64_tr_b16 v[186:187], v71
	v_bitop3_b32 v66, v66, s77, v85 bitop3:0x36
	v_mfma_f32_16x16x32_bf16 v[134:137], v[196:199], v[56:59], v[134:137]
	ds_read_b64_tr_b16 v[152:153], v133
	v_add_u32_e32 v64, s73, v64
	v_add_u32_e32 v66, s73, v66
	v_mfma_f32_16x16x32_bf16 v[138:141], v[200:203], v[56:59], v[138:141]
	ds_read_b64_tr_b16 v[64:65], v64
	ds_read_b64_tr_b16 v[66:67], v66
	v_mfma_f32_16x16x32_bf16 v[142:145], v[204:207], v[56:59], v[142:145]
	s_waitcnt lgkmcnt(14)
	v_mfma_f32_16x16x32_bf16 v[146:149], v[154:157], v[56:59], v[146:149]
	v_mfma_f32_16x16x32_bf16 v[56:59], v[158:161], v[56:59], v[60:63]
	s_nop 2
	v_or_b32_e32 v60, s78, v111
	v_lshl_or_b32 v71, v60, 8, v114
	v_or_b32_e32 v60, 4, v60
	v_bitop3_b32 v133, v71, s77, v117 bitop3:0x36
	v_bfe_u32 v83, v60, 2, 2
	v_add_u32_e32 v133, s73, v133
	ds_read_b64_tr_b16 v[154:155], v133
	v_bitop3_b32 v133, v83, v116, v113 bitop3:0x36
	v_lshl_or_b32 v85, v60, 8, v114
	v_lshlrev_b32_e32 v133, 4, v133
	v_bitop3_b32 v133, v133, s77, v85 bitop3:0x36
	v_add_u32_e32 v133, s73, v133
	ds_read_b64_tr_b16 v[156:157], v133
	v_bitop3_b32 v133, v71, s77, v119 bitop3:0x36
	v_add_u32_e32 v133, s73, v133
	ds_read_b64_tr_b16 v[158:159], v133
	v_bitop3_b32 v133, v83, v118, v113 bitop3:0x36
	v_lshlrev_b32_e32 v133, 4, v133
	v_bitop3_b32 v133, v133, s77, v85 bitop3:0x36
	v_add_u32_e32 v133, s73, v133
	s_waitcnt lgkmcnt(3)
	v_mfma_f32_16x16x32_bf16 v[64:67], v[64:67], v[52:55], v[72:75]
	ds_read_b64_tr_b16 v[160:161], v133
	v_bitop3_b32 v62, v83, v112, v113 bitop3:0x36
	v_lshlrev_b32_e32 v62, 4, v62
	v_bitop3_b32 v72, v71, s77, v121 bitop3:0x36
	v_add_u32_e32 v133, s73, v72
	v_mfma_f32_16x16x32_bf16 v[72:75], v[162:165], v[52:55], v[76:79]
	v_bitop3_b32 v60, v71, s77, v115 bitop3:0x36
	v_bitop3_b32 v62, v62, s77, v85 bitop3:0x36
	v_add_u32_e32 v60, s73, v60
	ds_read_b64_tr_b16 v[76:77], v133
	v_bitop3_b32 v133, v71, s77, v123 bitop3:0x36
	v_add_u32_e32 v133, s73, v133
	ds_read_b64_tr_b16 v[162:163], v133
	v_bitop3_b32 v133, v83, v122, v113 bitop3:0x36
	v_lshlrev_b32_e32 v133, 4, v133
	v_bitop3_b32 v133, v133, s77, v85 bitop3:0x36
	v_add_u32_e32 v133, s73, v133
	v_add_u32_e32 v62, s73, v62
	ds_read_b64_tr_b16 v[164:165], v133
	v_bitop3_b32 v133, v71, s77, v126 bitop3:0x36
	ds_read_b64_tr_b16 v[60:61], v60
	ds_read_b64_tr_b16 v[62:63], v62
	v_add_u32_e32 v133, s73, v133
	v_mfma_f32_16x16x32_bf16 v[146:149], v[150:153], v[52:55], v[146:149]
	ds_read_b64_tr_b16 v[150:151], v133
	v_bitop3_b32 v133, v83, v124, v113 bitop3:0x36
	v_bitop3_b32 v78, v83, v120, v113 bitop3:0x36
	v_mfma_f32_16x16x32_bf16 v[86:89], v[166:169], v[52:55], v[86:89]
	v_lshlrev_b32_e32 v78, 4, v78
	v_bitop3_b32 v78, v78, s77, v85 bitop3:0x36
	v_add_u32_e32 v78, s73, v78
	v_mfma_f32_16x16x32_bf16 v[134:137], v[170:173], v[52:55], v[134:137]
	ds_read_b64_tr_b16 v[78:79], v78
	v_mfma_f32_16x16x32_bf16 v[138:141], v[174:177], v[52:55], v[138:141]
	v_mfma_f32_16x16x32_bf16 v[142:145], v[180:183], v[52:55], v[142:145]
	v_mfma_f32_16x16x32_bf16 v[56:59], v[184:187], v[52:55], v[56:59]
	v_lshlrev_b32_e32 v52, 4, v133
	v_bitop3_b32 v52, v52, s77, v85 bitop3:0x36
	v_bitop3_b32 v54, v83, v127, v113 bitop3:0x36
	v_add_u32_e32 v52, s73, v52
	v_lshlrev_b32_e32 v54, 4, v54
	ds_read_b64_tr_b16 v[152:153], v52
	v_bitop3_b32 v52, v71, s77, v128 bitop3:0x36
	v_bitop3_b32 v54, v54, s77, v85 bitop3:0x36
	v_add_u32_e32 v52, s73, v52
	v_add_u32_e32 v54, s73, v54
	ds_read_b64_tr_b16 v[52:53], v52
	ds_read_b64_tr_b16 v[54:55], v54
	v_bitop3_b32 v71, v71, s77, v130 bitop3:0x36
	v_add_u32_e32 v71, s73, v71
	s_waitcnt lgkmcnt(5)
; __device__ __forceinline__ unsigned cvtpk(float lo, float hi) { f32x2_t v = {lo, hi}; bf16x2_t b = __builtin_convertvector(v, bf16x2_t); return __builtin_bit_cast(unsigned, b); }
; #define ATT_VLOAD(kk_, buf_) do { const unsigned r0_ = 32 * (ks0 + (kk_)) + 8 * kg + q4; _Pragma("unroll") for (int c = 0; c < 8; ++c) { \
;         vlo[buf_][c] = vtr(vbase + ((off_b(r0_, 2 * c + (p4 >> 1)) + 8 * (p4 & 1)) ^ par)); vhi[buf_][c] = vtr(vbase + ((off_b(r0_ + 4, 2 * c + (p4 >> 1)) + 8 * (p4 & 1)) ^ par)); } } while (0)
; __device__ __forceinline__ void attn_compute(LAS unsigned char* lds, const bf16x8 (&qf)[4], const AttnUnit& u, bf16* og, float* lse) {
;     ...
;     for (int kk = 0; kk < 5; ++kk) {
;         if (kk < 4) ATT_VLOAD(kk + 1, (kk + 1) & 1);
; #pragma unroll
;         for (int c = 0; c < 8; ++c) {
;             const s16x4 lo = vlo[kk & 1][c], hi = vhi[kk & 1][c];
;             const bf16x8 vf = (bf16x8){lo[0], lo[1], lo[2], lo[3], hi[0], hi[1], hi[2], hi[3]};
;             o[c] = __builtin_amdgcn_mfma_f32_16x16x32_bf16(vf, pf[kk], o[c], 0, 0, 0);
;         }
;     }
;     ...
;     const float rl = 1.0f / l;
;     bf16* op = og + qtok * 1024 + h * 128 + 4 * kg;
; #pragma unroll
;     for (int c = 0; c < 8; ++c) { v2u wv; wv.x = cvtpk(o[c][0] * rl, o[c][1] * rl); wv.y = cvtpk(o[c][2] * rl, o[c][3] * rl); *(v2u*)(op + 16 * c) = wv; }
;     if (kg == 0) lse[qtok * 8 + h] = mx + __builtin_amdgcn_logf(l);
	v_mfma_f32_16x16x32_bf16 v[60:63], v[60:63], v[48:51], v[64:67]
	v_mfma_f32_16x16x32_bf16 v[64:67], v[154:157], v[48:51], v[72:75]
	v_mfma_f32_16x16x32_bf16 v[72:75], v[158:161], v[48:51], v[86:89]
	s_nop 2
	ds_read_b64_tr_b16 v[86:87], v71
	v_bitop3_b32 v71, v83, v129, v113 bitop3:0x36
	v_lshlrev_b32_e32 v71, 4, v71
	v_bitop3_b32 v71, v71, s77, v85 bitop3:0x36
	v_add_u32_e32 v71, s73, v71
	ds_read_b64_tr_b16 v[88:89], v71
	s_waitcnt lgkmcnt(5)
	v_mfma_f32_16x16x32_bf16 v[76:79], v[76:79], v[48:51], v[134:137]
	v_mov_b32_e32 v85, v81
	v_mfma_f32_16x16x32_bf16 v[134:137], v[162:165], v[48:51], v[138:141]
	s_waitcnt lgkmcnt(4)
	v_mfma_f32_16x16x32_bf16 v[138:141], v[150:153], v[48:51], v[142:145]
	v_lshlrev_b64 v[150:151], s8, v[80:81]
	s_lshl_b32 s8, s76, 8
	s_waitcnt lgkmcnt(2)
	v_mfma_f32_16x16x32_bf16 v[142:145], v[52:55], v[48:51], v[146:149]
	v_add_f32_e32 v54, v69, v70
	v_div_scale_f32 v55, s[30:31], v54, v54, 1.0
	v_rcp_f32_e32 v69, v55
	s_waitcnt lgkmcnt(0)
	v_mfma_f32_16x16x32_bf16 v[48:51], v[86:89], v[48:51], v[56:59]
	v_lshl_add_u64 v[52:53], s[62:63], 0, v[150:151]
	s_nop 1
	v_fma_f32 v56, -v55, v69, 1.0
	v_fmac_f32_e32 v69, v56, v69
	v_div_scale_f32 v56, vcc, 1.0, v54, 1.0
	v_mul_f32_e32 v57, v56, v69
	v_fma_f32 v58, -v55, v57, v56
	v_fmac_f32_e32 v57, v58, v69
	v_fma_f32 v55, -v55, v57, v56
	v_div_fmas_f32 v55, v55, v69, v57
	v_lshlrev_b64 v[58:59], 11, v[52:53]
	v_div_fixup_f32 v56, v55, v54, 1.0
	v_lshl_add_u64 v[58:59], s[60:61], 0, v[58:59]
	v_lshl_add_u64 v[58:59], v[58:59], 0, s[8:9]
	v_pk_mul_f32 v[60:61], v[56:57], v[60:61] op_sel_hi:[0,1]
	v_pk_mul_f32 v[62:63], v[56:57], v[62:63] op_sel_hi:[0,1]
	v_lshl_add_u64 v[58:59], v[58:59], 0, v[84:85]
	v_cvt_pk_bf16_f32 v60, v60, v61
	v_cvt_pk_bf16_f32 v61, v62, v63
	global_store_dwordx2 v[58:59], v[60:61], off
	v_pk_mul_f32 v[60:61], v[56:57], v[64:65] op_sel_hi:[0,1]
	v_pk_mul_f32 v[62:63], v[56:57], v[66:67] op_sel_hi:[0,1]
	v_cvt_pk_bf16_f32 v60, v60, v61
	v_cvt_pk_bf16_f32 v61, v62, v63
	global_store_dwordx2 v[58:59], v[60:61], off offset:32
	v_pk_mul_f32 v[60:61], v[56:57], v[72:73] op_sel_hi:[0,1]
	v_pk_mul_f32 v[62:63], v[56:57], v[74:75] op_sel_hi:[0,1]
	v_cvt_pk_bf16_f32 v60, v60, v61
	v_cvt_pk_bf16_f32 v61, v62, v63
	global_store_dwordx2 v[58:59], v[60:61], off offset:64
	v_pk_mul_f32 v[60:61], v[56:57], v[76:77] op_sel_hi:[0,1]
	v_pk_mul_f32 v[62:63], v[56:57], v[78:79] op_sel_hi:[0,1]
	v_cvt_pk_bf16_f32 v60, v60, v61
	v_cvt_pk_bf16_f32 v61, v62, v63
	global_store_dwordx2 v[58:59], v[60:61], off offset:96
	v_pk_mul_f32 v[60:61], v[56:57], v[134:135] op_sel_hi:[0,1]
	v_pk_mul_f32 v[62:63], v[56:57], v[136:137] op_sel_hi:[0,1]
	v_cvt_pk_bf16_f32 v60, v60, v61
	v_cvt_pk_bf16_f32 v61, v62, v63
	global_store_dwordx2 v[58:59], v[60:61], off offset:128
	v_pk_mul_f32 v[60:61], v[56:57], v[138:139] op_sel_hi:[0,1]
	v_pk_mul_f32 v[62:63], v[56:57], v[140:141] op_sel_hi:[0,1]
	v_cvt_pk_bf16_f32 v60, v60, v61
	v_cvt_pk_bf16_f32 v61, v62, v63
	global_store_dwordx2 v[58:59], v[60:61], off offset:160
	v_pk_mul_f32 v[60:61], v[56:57], v[142:143] op_sel_hi:[0,1]
	v_pk_mul_f32 v[62:63], v[56:57], v[144:145] op_sel_hi:[0,1]
	v_pk_mul_f32 v[48:49], v[56:57], v[48:49] op_sel_hi:[0,1]
	v_pk_mul_f32 v[50:51], v[56:57], v[50:51] op_sel_hi:[0,1]
	v_cvt_pk_bf16_f32 v60, v60, v61
	v_cvt_pk_bf16_f32 v61, v62, v63
	v_cvt_pk_bf16_f32 v48, v48, v49
	v_cvt_pk_bf16_f32 v49, v50, v51
	global_store_dwordx2 v[58:59], v[60:61], off offset:192
	global_store_dwordx2 v[58:59], v[48:49], off offset:224
	s_and_saveexec_b64 s[60:61], s[6:7]
	s_cbranch_execz .LBB0_146
	v_log_f32_e32 v48, v54
	s_ashr_i32 s11, s10, 31
	s_lshl_b64 s[10:11], s[10:11], 20
	s_add_u32 s10, s0, s10
	v_add_f32_e32 v50, v68, v48
	s_addc_u32 s11, s1, s11
	v_lshlrev_b64 v[48:49], 5, v[52:53]
	v_lshl_add_u64 v[48:49], s[10:11], 0, v[48:49]
	s_lshl_b32 s8, s76, 2
	v_lshl_add_u64 v[48:49], v[48:49], 0, s[8:9]
	global_store_dword v[48:49], v50, off
	s_branch .LBB0_146
